# LDS-DMA BK=64 double-buffered K-loop (hand-written) for ev_in, ffup0, odin, ffup1 GEMMs + counted vmcnt in remaining GEMM loops
# speedup vs baseline: 1.0392x; 1.0392x over previous
.LBB0_260:
	s_mul_hi_i32 s0, s23, 0x2aaaaaab
	s_lshr_b32 s1, s0, 31
	s_ashr_i32 s4, s0, 4
	s_add_i32 s4, s4, s1
	s_mul_i32 s0, s4, 0x60
	s_sub_i32 s0, s23, s0
	s_lshl_b32 s13, s0, 7
	s_lshl_b32 s14, s4, 7
	v_lshl_or_b32 v64, v183, 3, v191
	v_and_b32_e32 v65, 63, v64
	v_lshrrev_b32_e32 v66, 3, v65
	v_lshrrev_b32_e32 v67, 4, v65
	v_xor_b32_e32 v67, v67, v65
	v_and_b32_e32 v67, 7, v67
	v_lshlrev_b32_e32 v67, 4, v67
	s_movk_i32 s99, 0x800
	v_mad_u32_u24 v112, v66, s99, v67
	v_xor_b32_e32 v68, 64, v112
	v_add_u32_e32 v113, 0x3c00, v68
	v_add_u32_e32 v114, 0x7800, v112
	v_add_u32_e32 v115, 0xb400, v68
	v_add_u32_e32 v116, 0x10000, v112
	v_add_u32_e32 v117, 0x13c00, v68
	v_add_u32_e32 v118, 0x17800, v112
	v_add_u32_e32 v119, 0x1b400, v68
	v_and_b32_e32 v69, 31, v64
	v_bfe_u32 v70, v64, 5, 1
	v_bfe_u32 v71, v64, 1, 3
	v_xor_b32_e32 v71, v71, v70
	v_lshlrev_b32_e32 v71, 4, v71
	v_bfe_u32 v72, v64, 7, 1
	v_lshl_or_b32 v72, v72, 6, v69
	v_lshl_add_u32 v120, v72, 7, v71
	v_bfe_u32 v73, v64, 6, 1
	v_lshl_or_b32 v73, v73, 6, v69
	v_lshl_add_u32 v124, v73, 7, v71
	v_add_u32_e32 v124, 0x4000, v124
	v_xor_b32_e32 v121, 32, v120
	v_xor_b32_e32 v125, 32, v124
	v_xor_b32_e32 v122, 64, v120
	v_xor_b32_e32 v126, 64, v124
	v_xor_b32_e32 v123, 96, v120
	v_xor_b32_e32 v127, 96, v124
	v_lshrrev_b32_e32 v74, 6, v64
	s_nop 0
	v_readfirstlane_b32 s100, v74
	s_nop 3
	s_lshl_b32 s98, s100, 13
	s_mov_b32 s101, 0x0
	s_mov_b32 s99, s14
	s_cmp_lt_u32 s100, 2
	s_cmov_b32 s101, 0xb171900
	s_cmov_b32 s99, s13
	s_and_b32 s100, s100, 1
	s_lshl_b32 s100, s100, 6
	s_add_u32 s99, s99, s100
	s_mul_i32 s99, s99, 0x800
	s_add_u32 s99, s99, s101
	s_add_u32 s0, s90, s99
	s_addc_u32 s1, s91, 0
	s_add_u32 m0, s98, 0x0
	s_nop 0
	global_load_lds_dwordx4 v112, s[0:1] offset:0
	global_load_lds_dwordx4 v113, s[0:1] offset:1024
	global_load_lds_dwordx4 v114, s[0:1] offset:2048
	global_load_lds_dwordx4 v115, s[0:1] offset:3072
	s_add_u32 m0, s98, 0x1000
	s_nop 0
	global_load_lds_dwordx4 v116, s[0:1] offset:0
	global_load_lds_dwordx4 v117, s[0:1] offset:1024
	global_load_lds_dwordx4 v118, s[0:1] offset:2048
	global_load_lds_dwordx4 v119, s[0:1] offset:3072
	s_add_u32 s0, s0, 0x80
	s_addc_u32 s1, s1, 0
	s_add_u32 m0, s98, 0x8000
	s_nop 0
	global_load_lds_dwordx4 v112, s[0:1] offset:0
	global_load_lds_dwordx4 v113, s[0:1] offset:1024
	global_load_lds_dwordx4 v114, s[0:1] offset:2048
	global_load_lds_dwordx4 v115, s[0:1] offset:3072
	s_add_u32 m0, s98, 0x9000
	s_nop 0
	global_load_lds_dwordx4 v116, s[0:1] offset:0
	global_load_lds_dwordx4 v117, s[0:1] offset:1024
	global_load_lds_dwordx4 v118, s[0:1] offset:2048
	global_load_lds_dwordx4 v119, s[0:1] offset:3072
	s_add_u32 s0, s0, 0x80
	s_addc_u32 s1, s1, 0
	v_mov_b32_e32 v48, 0
	v_mov_b32_e32 v49, 0
	v_mov_b32_e32 v50, 0
	v_mov_b32_e32 v51, 0
	v_mov_b32_e32 v52, 0
	v_mov_b32_e32 v53, 0
	v_mov_b32_e32 v54, 0
	v_mov_b32_e32 v55, 0
	v_mov_b32_e32 v56, 0
	v_mov_b32_e32 v57, 0
	v_mov_b32_e32 v58, 0
	v_mov_b32_e32 v59, 0
	v_mov_b32_e32 v60, 0
	v_mov_b32_e32 v61, 0
	v_mov_b32_e32 v62, 0
	v_mov_b32_e32 v63, 0
	v_mov_b32_e32 v16, 0
	v_mov_b32_e32 v17, 0
	v_mov_b32_e32 v18, 0
	v_mov_b32_e32 v19, 0
	v_mov_b32_e32 v20, 0
	v_mov_b32_e32 v21, 0
	v_mov_b32_e32 v22, 0
	v_mov_b32_e32 v23, 0
	v_mov_b32_e32 v24, 0
	v_mov_b32_e32 v25, 0
	v_mov_b32_e32 v26, 0
	v_mov_b32_e32 v27, 0
	v_mov_b32_e32 v28, 0
	v_mov_b32_e32 v29, 0
	v_mov_b32_e32 v30, 0
	v_mov_b32_e32 v31, 0
	v_mov_b32_e32 v32, 0
	v_mov_b32_e32 v33, 0
	v_mov_b32_e32 v34, 0
	v_mov_b32_e32 v35, 0
	v_mov_b32_e32 v36, 0
	v_mov_b32_e32 v37, 0
	v_mov_b32_e32 v38, 0
	v_mov_b32_e32 v39, 0
	v_mov_b32_e32 v40, 0
	v_mov_b32_e32 v41, 0
	v_mov_b32_e32 v42, 0
	v_mov_b32_e32 v43, 0
	v_mov_b32_e32 v44, 0
	v_mov_b32_e32 v45, 0
	v_mov_b32_e32 v46, 0
	v_mov_b32_e32 v47, 0
	v_mov_b32_e32 v0, 0
	v_mov_b32_e32 v1, 0
	v_mov_b32_e32 v2, 0
	v_mov_b32_e32 v3, 0
	v_mov_b32_e32 v4, 0
	v_mov_b32_e32 v5, 0
	v_mov_b32_e32 v6, 0
	v_mov_b32_e32 v7, 0
	v_mov_b32_e32 v8, 0
	v_mov_b32_e32 v9, 0
	v_mov_b32_e32 v10, 0
	v_mov_b32_e32 v11, 0
	v_mov_b32_e32 v12, 0
	v_mov_b32_e32 v13, 0
	v_mov_b32_e32 v14, 0
	v_mov_b32_e32 v15, 0
	s_movk_i32 s2, 7
	s_waitcnt vmcnt(8)
.Lg1_loop:
	s_waitcnt vmcnt(8)
	s_barrier
	ds_read_b128 v[64:67], v120 offset:0
	ds_read_b128 v[72:75], v124 offset:0
	ds_read_b128 v[76:79], v124 offset:4096
	ds_read_b128 v[68:71], v120 offset:4096
	ds_read_b128 v[80:83], v121 offset:0
	ds_read_b128 v[88:91], v125 offset:0
	ds_read_b128 v[92:95], v125 offset:4096
	ds_read_b128 v[84:87], v121 offset:4096
	s_waitcnt lgkmcnt(4)
	v_mfma_f32_32x32x16_bf16 v[48:63], v[64:67], v[72:75], v[48:63]
	ds_read_b128 v[96:99], v122 offset:0
	v_mfma_f32_32x32x16_bf16 v[16:31], v[64:67], v[76:79], v[16:31]
	ds_read_b128 v[104:107], v126 offset:0
	v_mfma_f32_32x32x16_bf16 v[32:47], v[68:71], v[72:75], v[32:47]
	ds_read_b128 v[108:111], v126 offset:4096
	v_mfma_f32_32x32x16_bf16 v[0:15], v[68:71], v[76:79], v[0:15]
	ds_read_b128 v[100:103], v122 offset:4096
	s_waitcnt lgkmcnt(4)
	v_mfma_f32_32x32x16_bf16 v[48:63], v[80:83], v[88:91], v[48:63]
	ds_read_b128 v[64:67], v123 offset:0
	v_mfma_f32_32x32x16_bf16 v[16:31], v[80:83], v[92:95], v[16:31]
	ds_read_b128 v[72:75], v127 offset:0
	v_mfma_f32_32x32x16_bf16 v[32:47], v[84:87], v[88:91], v[32:47]
	ds_read_b128 v[76:79], v127 offset:4096
	v_mfma_f32_32x32x16_bf16 v[0:15], v[84:87], v[92:95], v[0:15]
	ds_read_b128 v[68:71], v123 offset:4096
	s_waitcnt lgkmcnt(4)
	v_mfma_f32_32x32x16_bf16 v[48:63], v[96:99], v[104:107], v[48:63]
	v_mfma_f32_32x32x16_bf16 v[16:31], v[96:99], v[108:111], v[16:31]
	v_mfma_f32_32x32x16_bf16 v[32:47], v[100:103], v[104:107], v[32:47]
	v_mfma_f32_32x32x16_bf16 v[0:15], v[100:103], v[108:111], v[0:15]
	s_waitcnt lgkmcnt(0)
	v_mfma_f32_32x32x16_bf16 v[48:63], v[64:67], v[72:75], v[48:63]
	v_mfma_f32_32x32x16_bf16 v[16:31], v[64:67], v[76:79], v[16:31]
	v_mfma_f32_32x32x16_bf16 v[32:47], v[68:71], v[72:75], v[32:47]
	v_mfma_f32_32x32x16_bf16 v[0:15], v[68:71], v[76:79], v[0:15]
	s_barrier
	s_add_u32 m0, s98, 0x0
	s_nop 0
	global_load_lds_dwordx4 v112, s[0:1] offset:0
	global_load_lds_dwordx4 v113, s[0:1] offset:1024
	global_load_lds_dwordx4 v114, s[0:1] offset:2048
	global_load_lds_dwordx4 v115, s[0:1] offset:3072
	s_add_u32 m0, s98, 0x1000
	s_nop 0
	global_load_lds_dwordx4 v116, s[0:1] offset:0
	global_load_lds_dwordx4 v117, s[0:1] offset:1024
	global_load_lds_dwordx4 v118, s[0:1] offset:2048
	global_load_lds_dwordx4 v119, s[0:1] offset:3072
	s_add_u32 s0, s0, 0x80
	s_addc_u32 s1, s1, 0
	s_waitcnt vmcnt(8)
	s_barrier
	ds_read_b128 v[64:67], v120 offset:32768
	ds_read_b128 v[72:75], v124 offset:32768
	ds_read_b128 v[76:79], v124 offset:36864
	ds_read_b128 v[68:71], v120 offset:36864
	ds_read_b128 v[80:83], v121 offset:32768
	ds_read_b128 v[88:91], v125 offset:32768
	ds_read_b128 v[92:95], v125 offset:36864
	ds_read_b128 v[84:87], v121 offset:36864
	s_waitcnt lgkmcnt(4)
	v_mfma_f32_32x32x16_bf16 v[48:63], v[64:67], v[72:75], v[48:63]
	ds_read_b128 v[96:99], v122 offset:32768
	v_mfma_f32_32x32x16_bf16 v[16:31], v[64:67], v[76:79], v[16:31]
	ds_read_b128 v[104:107], v126 offset:32768
	v_mfma_f32_32x32x16_bf16 v[32:47], v[68:71], v[72:75], v[32:47]
	ds_read_b128 v[108:111], v126 offset:36864
	v_mfma_f32_32x32x16_bf16 v[0:15], v[68:71], v[76:79], v[0:15]
	ds_read_b128 v[100:103], v122 offset:36864
	s_waitcnt lgkmcnt(4)
	v_mfma_f32_32x32x16_bf16 v[48:63], v[80:83], v[88:91], v[48:63]
	ds_read_b128 v[64:67], v123 offset:32768
	v_mfma_f32_32x32x16_bf16 v[16:31], v[80:83], v[92:95], v[16:31]
	ds_read_b128 v[72:75], v127 offset:32768
	v_mfma_f32_32x32x16_bf16 v[32:47], v[84:87], v[88:91], v[32:47]
	ds_read_b128 v[76:79], v127 offset:36864
	v_mfma_f32_32x32x16_bf16 v[0:15], v[84:87], v[92:95], v[0:15]
	ds_read_b128 v[68:71], v123 offset:36864
	s_waitcnt lgkmcnt(4)
	v_mfma_f32_32x32x16_bf16 v[48:63], v[96:99], v[104:107], v[48:63]
	v_mfma_f32_32x32x16_bf16 v[16:31], v[96:99], v[108:111], v[16:31]
	v_mfma_f32_32x32x16_bf16 v[32:47], v[100:103], v[104:107], v[32:47]
	v_mfma_f32_32x32x16_bf16 v[0:15], v[100:103], v[108:111], v[0:15]
	s_waitcnt lgkmcnt(0)
	v_mfma_f32_32x32x16_bf16 v[48:63], v[64:67], v[72:75], v[48:63]
	v_mfma_f32_32x32x16_bf16 v[16:31], v[64:67], v[76:79], v[16:31]
	v_mfma_f32_32x32x16_bf16 v[32:47], v[68:71], v[72:75], v[32:47]
	v_mfma_f32_32x32x16_bf16 v[0:15], v[68:71], v[76:79], v[0:15]
	s_barrier
	s_add_u32 m0, s98, 0x8000
	s_nop 0
	global_load_lds_dwordx4 v112, s[0:1] offset:0
	global_load_lds_dwordx4 v113, s[0:1] offset:1024
	global_load_lds_dwordx4 v114, s[0:1] offset:2048
	global_load_lds_dwordx4 v115, s[0:1] offset:3072
	s_add_u32 m0, s98, 0x9000
	s_nop 0
	global_load_lds_dwordx4 v116, s[0:1] offset:0
	global_load_lds_dwordx4 v117, s[0:1] offset:1024
	global_load_lds_dwordx4 v118, s[0:1] offset:2048
	global_load_lds_dwordx4 v119, s[0:1] offset:3072
	s_add_u32 s0, s0, 0x80
	s_addc_u32 s1, s1, 0
	s_sub_u32 s2, s2, 1
	s_cmp_lg_u32 s2, 0
	s_cbranch_scc1 .Lg1_loop
	s_waitcnt vmcnt(8)
	s_barrier
	ds_read_b128 v[64:67], v120 offset:0
	ds_read_b128 v[72:75], v124 offset:0
	ds_read_b128 v[76:79], v124 offset:4096
	ds_read_b128 v[68:71], v120 offset:4096
	ds_read_b128 v[80:83], v121 offset:0
	ds_read_b128 v[88:91], v125 offset:0
	ds_read_b128 v[92:95], v125 offset:4096
	ds_read_b128 v[84:87], v121 offset:4096
	s_waitcnt lgkmcnt(4)
	v_mfma_f32_32x32x16_bf16 v[48:63], v[64:67], v[72:75], v[48:63]
	ds_read_b128 v[96:99], v122 offset:0
	v_mfma_f32_32x32x16_bf16 v[16:31], v[64:67], v[76:79], v[16:31]
	ds_read_b128 v[104:107], v126 offset:0
	v_mfma_f32_32x32x16_bf16 v[32:47], v[68:71], v[72:75], v[32:47]
	ds_read_b128 v[108:111], v126 offset:4096
	v_mfma_f32_32x32x16_bf16 v[0:15], v[68:71], v[76:79], v[0:15]
	ds_read_b128 v[100:103], v122 offset:4096
	s_waitcnt lgkmcnt(4)
	v_mfma_f32_32x32x16_bf16 v[48:63], v[80:83], v[88:91], v[48:63]
	ds_read_b128 v[64:67], v123 offset:0
	v_mfma_f32_32x32x16_bf16 v[16:31], v[80:83], v[92:95], v[16:31]
	ds_read_b128 v[72:75], v127 offset:0
	v_mfma_f32_32x32x16_bf16 v[32:47], v[84:87], v[88:91], v[32:47]
	ds_read_b128 v[76:79], v127 offset:4096
	v_mfma_f32_32x32x16_bf16 v[0:15], v[84:87], v[92:95], v[0:15]
	ds_read_b128 v[68:71], v123 offset:4096
	s_waitcnt lgkmcnt(4)
	v_mfma_f32_32x32x16_bf16 v[48:63], v[96:99], v[104:107], v[48:63]
	v_mfma_f32_32x32x16_bf16 v[16:31], v[96:99], v[108:111], v[16:31]
	v_mfma_f32_32x32x16_bf16 v[32:47], v[100:103], v[104:107], v[32:47]
	v_mfma_f32_32x32x16_bf16 v[0:15], v[100:103], v[108:111], v[0:15]
	s_waitcnt lgkmcnt(0)
	v_mfma_f32_32x32x16_bf16 v[48:63], v[64:67], v[72:75], v[48:63]
	v_mfma_f32_32x32x16_bf16 v[16:31], v[64:67], v[76:79], v[16:31]
	v_mfma_f32_32x32x16_bf16 v[32:47], v[68:71], v[72:75], v[32:47]
	v_mfma_f32_32x32x16_bf16 v[0:15], v[68:71], v[76:79], v[0:15]
	s_barrier
	s_waitcnt vmcnt(0)
	s_barrier
	ds_read_b128 v[64:67], v120 offset:32768
	ds_read_b128 v[72:75], v124 offset:32768
	ds_read_b128 v[76:79], v124 offset:36864
	ds_read_b128 v[68:71], v120 offset:36864
	ds_read_b128 v[80:83], v121 offset:32768
	ds_read_b128 v[88:91], v125 offset:32768
	ds_read_b128 v[92:95], v125 offset:36864
	ds_read_b128 v[84:87], v121 offset:36864
	s_waitcnt lgkmcnt(4)
	v_mfma_f32_32x32x16_bf16 v[48:63], v[64:67], v[72:75], v[48:63]
	ds_read_b128 v[96:99], v122 offset:32768
	v_mfma_f32_32x32x16_bf16 v[16:31], v[64:67], v[76:79], v[16:31]
	ds_read_b128 v[104:107], v126 offset:32768
	v_mfma_f32_32x32x16_bf16 v[32:47], v[68:71], v[72:75], v[32:47]
	ds_read_b128 v[108:111], v126 offset:36864
	v_mfma_f32_32x32x16_bf16 v[0:15], v[68:71], v[76:79], v[0:15]
	ds_read_b128 v[100:103], v122 offset:36864
	s_waitcnt lgkmcnt(4)
	v_mfma_f32_32x32x16_bf16 v[48:63], v[80:83], v[88:91], v[48:63]
	ds_read_b128 v[64:67], v123 offset:32768
	v_mfma_f32_32x32x16_bf16 v[16:31], v[80:83], v[92:95], v[16:31]
	ds_read_b128 v[72:75], v127 offset:32768
	v_mfma_f32_32x32x16_bf16 v[32:47], v[84:87], v[88:91], v[32:47]
	ds_read_b128 v[76:79], v127 offset:36864
	v_mfma_f32_32x32x16_bf16 v[0:15], v[84:87], v[92:95], v[0:15]
	ds_read_b128 v[68:71], v123 offset:36864
	s_waitcnt lgkmcnt(4)
	v_mfma_f32_32x32x16_bf16 v[48:63], v[96:99], v[104:107], v[48:63]
	v_mfma_f32_32x32x16_bf16 v[16:31], v[96:99], v[108:111], v[16:31]
	v_mfma_f32_32x32x16_bf16 v[32:47], v[100:103], v[104:107], v[32:47]
	v_mfma_f32_32x32x16_bf16 v[0:15], v[100:103], v[108:111], v[0:15]
	s_waitcnt lgkmcnt(0)
	v_mfma_f32_32x32x16_bf16 v[48:63], v[64:67], v[72:75], v[48:63]
	v_mfma_f32_32x32x16_bf16 v[16:31], v[64:67], v[76:79], v[16:31]
	v_mfma_f32_32x32x16_bf16 v[32:47], v[68:71], v[72:75], v[32:47]
	v_mfma_f32_32x32x16_bf16 v[0:15], v[68:71], v[76:79], v[0:15]
	s_nop 7
	s_nop 7
	s_branch .LBB0_268

.LBB0_1035:
	s_mul_hi_i32 s2, s57, 0x2aaaaaab
	s_lshr_b32 s3, s2, 31
	s_ashr_i32 s2, s2, 4
	s_add_i32 s2, s2, s3
	s_mul_i32 s3, s2, 0x60
	s_sub_i32 s3, s57, s3
	s_lshl_b32 s48, s3, 7
	s_lshl_b32 s49, s2, 7
	v_lshl_or_b32 v64, v183, 3, v191
	v_and_b32_e32 v65, 63, v64
	v_lshrrev_b32_e32 v66, 3, v65
	v_lshrrev_b32_e32 v67, 4, v65
	v_xor_b32_e32 v67, v67, v65
	v_and_b32_e32 v67, 7, v67
	v_lshlrev_b32_e32 v67, 4, v67
	s_movk_i32 s99, 0x800
	v_mad_u32_u24 v112, v66, s99, v67
	v_xor_b32_e32 v68, 64, v112
	v_add_u32_e32 v113, 0x3c00, v68
	v_add_u32_e32 v114, 0x7800, v112
	v_add_u32_e32 v115, 0xb400, v68
	v_add_u32_e32 v116, 0x10000, v112
	v_add_u32_e32 v117, 0x13c00, v68
	v_add_u32_e32 v118, 0x17800, v112
	v_add_u32_e32 v119, 0x1b400, v68
	v_and_b32_e32 v69, 31, v64
	v_bfe_u32 v70, v64, 5, 1
	v_bfe_u32 v71, v64, 1, 3
	v_xor_b32_e32 v71, v71, v70
	v_lshlrev_b32_e32 v71, 4, v71
	v_bfe_u32 v72, v64, 7, 1
	v_lshl_or_b32 v72, v72, 6, v69
	v_lshl_add_u32 v120, v72, 7, v71
	v_bfe_u32 v73, v64, 6, 1
	v_lshl_or_b32 v73, v73, 6, v69
	v_lshl_add_u32 v124, v73, 7, v71
	v_add_u32_e32 v124, 0x4000, v124
	v_xor_b32_e32 v121, 32, v120
	v_xor_b32_e32 v125, 32, v124
	v_xor_b32_e32 v122, 64, v120
	v_xor_b32_e32 v126, 64, v124
	v_xor_b32_e32 v123, 96, v120
	v_xor_b32_e32 v127, 96, v124
	v_lshrrev_b32_e32 v74, 6, v64
	s_nop 0
	v_readfirstlane_b32 s100, v74
	s_nop 3
	s_lshl_b32 s98, s100, 13
	s_mov_b32 s101, 0xb40000
	s_mov_b32 s99, s49
	s_cmp_lt_u32 s100, 2
	s_cmov_b32 s101, 0xb171900
	s_cmov_b32 s99, s48
	s_and_b32 s100, s100, 1
	s_lshl_b32 s100, s100, 6
	s_add_u32 s99, s99, s100
	s_mul_i32 s99, s99, 0x800
	s_add_u32 s99, s99, s101
	s_add_u32 s2, s90, s99
	s_addc_u32 s3, s91, 0
	s_add_u32 m0, s98, 0x0
	s_nop 0
	global_load_lds_dwordx4 v112, s[2:3] offset:0
	global_load_lds_dwordx4 v113, s[2:3] offset:1024
	global_load_lds_dwordx4 v114, s[2:3] offset:2048
	global_load_lds_dwordx4 v115, s[2:3] offset:3072
	s_add_u32 m0, s98, 0x1000
	s_nop 0
	global_load_lds_dwordx4 v116, s[2:3] offset:0
	global_load_lds_dwordx4 v117, s[2:3] offset:1024
	global_load_lds_dwordx4 v118, s[2:3] offset:2048
	global_load_lds_dwordx4 v119, s[2:3] offset:3072
	s_add_u32 s2, s2, 0x80
	s_addc_u32 s3, s3, 0
	s_add_u32 m0, s98, 0x8000
	s_nop 0
	global_load_lds_dwordx4 v112, s[2:3] offset:0
	global_load_lds_dwordx4 v113, s[2:3] offset:1024
	global_load_lds_dwordx4 v114, s[2:3] offset:2048
	global_load_lds_dwordx4 v115, s[2:3] offset:3072
	s_add_u32 m0, s98, 0x9000
	s_nop 0
	global_load_lds_dwordx4 v116, s[2:3] offset:0
	global_load_lds_dwordx4 v117, s[2:3] offset:1024
	global_load_lds_dwordx4 v118, s[2:3] offset:2048
	global_load_lds_dwordx4 v119, s[2:3] offset:3072
	s_add_u32 s2, s2, 0x80
	s_addc_u32 s3, s3, 0
	v_mov_b32_e32 v48, 0
	v_mov_b32_e32 v49, 0
	v_mov_b32_e32 v50, 0
	v_mov_b32_e32 v51, 0
	v_mov_b32_e32 v52, 0
	v_mov_b32_e32 v53, 0
	v_mov_b32_e32 v54, 0
	v_mov_b32_e32 v55, 0
	v_mov_b32_e32 v56, 0
	v_mov_b32_e32 v57, 0
	v_mov_b32_e32 v58, 0
	v_mov_b32_e32 v59, 0
	v_mov_b32_e32 v60, 0
	v_mov_b32_e32 v61, 0
	v_mov_b32_e32 v62, 0
	v_mov_b32_e32 v63, 0
	v_mov_b32_e32 v32, 0
	v_mov_b32_e32 v33, 0
	v_mov_b32_e32 v34, 0
	v_mov_b32_e32 v35, 0
	v_mov_b32_e32 v36, 0
	v_mov_b32_e32 v37, 0
	v_mov_b32_e32 v38, 0
	v_mov_b32_e32 v39, 0
	v_mov_b32_e32 v40, 0
	v_mov_b32_e32 v41, 0
	v_mov_b32_e32 v42, 0
	v_mov_b32_e32 v43, 0
	v_mov_b32_e32 v44, 0
	v_mov_b32_e32 v45, 0
	v_mov_b32_e32 v46, 0
	v_mov_b32_e32 v47, 0
	v_mov_b32_e32 v16, 0
	v_mov_b32_e32 v17, 0
	v_mov_b32_e32 v18, 0
	v_mov_b32_e32 v19, 0
	v_mov_b32_e32 v20, 0
	v_mov_b32_e32 v21, 0
	v_mov_b32_e32 v22, 0
	v_mov_b32_e32 v23, 0
	v_mov_b32_e32 v24, 0
	v_mov_b32_e32 v25, 0
	v_mov_b32_e32 v26, 0
	v_mov_b32_e32 v27, 0
	v_mov_b32_e32 v28, 0
	v_mov_b32_e32 v29, 0
	v_mov_b32_e32 v30, 0
	v_mov_b32_e32 v31, 0
	v_mov_b32_e32 v0, 0
	v_mov_b32_e32 v1, 0
	v_mov_b32_e32 v2, 0
	v_mov_b32_e32 v3, 0
	v_mov_b32_e32 v4, 0
	v_mov_b32_e32 v5, 0
	v_mov_b32_e32 v6, 0
	v_mov_b32_e32 v7, 0
	v_mov_b32_e32 v8, 0
	v_mov_b32_e32 v9, 0
	v_mov_b32_e32 v10, 0
	v_mov_b32_e32 v11, 0
	v_mov_b32_e32 v12, 0
	v_mov_b32_e32 v13, 0
	v_mov_b32_e32 v14, 0
	v_mov_b32_e32 v15, 0
	s_movk_i32 s6, 7
	s_waitcnt vmcnt(8)
.Lg2_loop:
	s_waitcnt vmcnt(8)
	s_barrier
	ds_read_b128 v[64:67], v120 offset:0
	ds_read_b128 v[72:75], v124 offset:0
	ds_read_b128 v[76:79], v124 offset:4096
	ds_read_b128 v[68:71], v120 offset:4096
	ds_read_b128 v[80:83], v121 offset:0
	ds_read_b128 v[88:91], v125 offset:0
	ds_read_b128 v[92:95], v125 offset:4096
	ds_read_b128 v[84:87], v121 offset:4096
	s_waitcnt lgkmcnt(4)
	v_mfma_f32_32x32x16_bf16 v[48:63], v[64:67], v[72:75], v[48:63]
	ds_read_b128 v[96:99], v122 offset:0
	v_mfma_f32_32x32x16_bf16 v[32:47], v[64:67], v[76:79], v[32:47]
	ds_read_b128 v[104:107], v126 offset:0
	v_mfma_f32_32x32x16_bf16 v[16:31], v[68:71], v[72:75], v[16:31]
	ds_read_b128 v[108:111], v126 offset:4096
	v_mfma_f32_32x32x16_bf16 v[0:15], v[68:71], v[76:79], v[0:15]
	ds_read_b128 v[100:103], v122 offset:4096
	s_waitcnt lgkmcnt(4)
	v_mfma_f32_32x32x16_bf16 v[48:63], v[80:83], v[88:91], v[48:63]
	ds_read_b128 v[64:67], v123 offset:0
	v_mfma_f32_32x32x16_bf16 v[32:47], v[80:83], v[92:95], v[32:47]
	ds_read_b128 v[72:75], v127 offset:0
	v_mfma_f32_32x32x16_bf16 v[16:31], v[84:87], v[88:91], v[16:31]
	ds_read_b128 v[76:79], v127 offset:4096
	v_mfma_f32_32x32x16_bf16 v[0:15], v[84:87], v[92:95], v[0:15]
	ds_read_b128 v[68:71], v123 offset:4096
	s_waitcnt lgkmcnt(4)
	v_mfma_f32_32x32x16_bf16 v[48:63], v[96:99], v[104:107], v[48:63]
	v_mfma_f32_32x32x16_bf16 v[32:47], v[96:99], v[108:111], v[32:47]
	v_mfma_f32_32x32x16_bf16 v[16:31], v[100:103], v[104:107], v[16:31]
	v_mfma_f32_32x32x16_bf16 v[0:15], v[100:103], v[108:111], v[0:15]
	s_waitcnt lgkmcnt(0)
	v_mfma_f32_32x32x16_bf16 v[48:63], v[64:67], v[72:75], v[48:63]
	v_mfma_f32_32x32x16_bf16 v[32:47], v[64:67], v[76:79], v[32:47]
	v_mfma_f32_32x32x16_bf16 v[16:31], v[68:71], v[72:75], v[16:31]
	v_mfma_f32_32x32x16_bf16 v[0:15], v[68:71], v[76:79], v[0:15]
	s_barrier
	s_add_u32 m0, s98, 0x0
	s_nop 0
	global_load_lds_dwordx4 v112, s[2:3] offset:0
	global_load_lds_dwordx4 v113, s[2:3] offset:1024
	global_load_lds_dwordx4 v114, s[2:3] offset:2048
	global_load_lds_dwordx4 v115, s[2:3] offset:3072
	s_add_u32 m0, s98, 0x1000
	s_nop 0
	global_load_lds_dwordx4 v116, s[2:3] offset:0
	global_load_lds_dwordx4 v117, s[2:3] offset:1024
	global_load_lds_dwordx4 v118, s[2:3] offset:2048
	global_load_lds_dwordx4 v119, s[2:3] offset:3072
	s_add_u32 s2, s2, 0x80
	s_addc_u32 s3, s3, 0
	s_waitcnt vmcnt(8)
	s_barrier
	ds_read_b128 v[64:67], v120 offset:32768
	ds_read_b128 v[72:75], v124 offset:32768
	ds_read_b128 v[76:79], v124 offset:36864
	ds_read_b128 v[68:71], v120 offset:36864
	ds_read_b128 v[80:83], v121 offset:32768
	ds_read_b128 v[88:91], v125 offset:32768
	ds_read_b128 v[92:95], v125 offset:36864
	ds_read_b128 v[84:87], v121 offset:36864
	s_waitcnt lgkmcnt(4)
	v_mfma_f32_32x32x16_bf16 v[48:63], v[64:67], v[72:75], v[48:63]
	ds_read_b128 v[96:99], v122 offset:32768
	v_mfma_f32_32x32x16_bf16 v[32:47], v[64:67], v[76:79], v[32:47]
	ds_read_b128 v[104:107], v126 offset:32768
	v_mfma_f32_32x32x16_bf16 v[16:31], v[68:71], v[72:75], v[16:31]
	ds_read_b128 v[108:111], v126 offset:36864
	v_mfma_f32_32x32x16_bf16 v[0:15], v[68:71], v[76:79], v[0:15]
	ds_read_b128 v[100:103], v122 offset:36864
	s_waitcnt lgkmcnt(4)
	v_mfma_f32_32x32x16_bf16 v[48:63], v[80:83], v[88:91], v[48:63]
	ds_read_b128 v[64:67], v123 offset:32768
	v_mfma_f32_32x32x16_bf16 v[32:47], v[80:83], v[92:95], v[32:47]
	ds_read_b128 v[72:75], v127 offset:32768
	v_mfma_f32_32x32x16_bf16 v[16:31], v[84:87], v[88:91], v[16:31]
	ds_read_b128 v[76:79], v127 offset:36864
	v_mfma_f32_32x32x16_bf16 v[0:15], v[84:87], v[92:95], v[0:15]
	ds_read_b128 v[68:71], v123 offset:36864
	s_waitcnt lgkmcnt(4)
	v_mfma_f32_32x32x16_bf16 v[48:63], v[96:99], v[104:107], v[48:63]
	v_mfma_f32_32x32x16_bf16 v[32:47], v[96:99], v[108:111], v[32:47]
	v_mfma_f32_32x32x16_bf16 v[16:31], v[100:103], v[104:107], v[16:31]
	v_mfma_f32_32x32x16_bf16 v[0:15], v[100:103], v[108:111], v[0:15]
	s_waitcnt lgkmcnt(0)
	v_mfma_f32_32x32x16_bf16 v[48:63], v[64:67], v[72:75], v[48:63]
	v_mfma_f32_32x32x16_bf16 v[32:47], v[64:67], v[76:79], v[32:47]
	v_mfma_f32_32x32x16_bf16 v[16:31], v[68:71], v[72:75], v[16:31]
	v_mfma_f32_32x32x16_bf16 v[0:15], v[68:71], v[76:79], v[0:15]
	s_barrier
	s_add_u32 m0, s98, 0x8000
	s_nop 0
	global_load_lds_dwordx4 v112, s[2:3] offset:0
	global_load_lds_dwordx4 v113, s[2:3] offset:1024
	global_load_lds_dwordx4 v114, s[2:3] offset:2048
	global_load_lds_dwordx4 v115, s[2:3] offset:3072
	s_add_u32 m0, s98, 0x9000
	s_nop 0
	global_load_lds_dwordx4 v116, s[2:3] offset:0
	global_load_lds_dwordx4 v117, s[2:3] offset:1024
	global_load_lds_dwordx4 v118, s[2:3] offset:2048
	global_load_lds_dwordx4 v119, s[2:3] offset:3072
	s_add_u32 s2, s2, 0x80
	s_addc_u32 s3, s3, 0
	s_sub_u32 s6, s6, 1
	s_cmp_lg_u32 s6, 0
	s_cbranch_scc1 .Lg2_loop
	s_waitcnt vmcnt(8)
	s_barrier
	ds_read_b128 v[64:67], v120 offset:0
	ds_read_b128 v[72:75], v124 offset:0
	ds_read_b128 v[76:79], v124 offset:4096
	ds_read_b128 v[68:71], v120 offset:4096
	ds_read_b128 v[80:83], v121 offset:0
	ds_read_b128 v[88:91], v125 offset:0
	ds_read_b128 v[92:95], v125 offset:4096
	ds_read_b128 v[84:87], v121 offset:4096
	s_waitcnt lgkmcnt(4)
	v_mfma_f32_32x32x16_bf16 v[48:63], v[64:67], v[72:75], v[48:63]
	ds_read_b128 v[96:99], v122 offset:0
	v_mfma_f32_32x32x16_bf16 v[32:47], v[64:67], v[76:79], v[32:47]
	ds_read_b128 v[104:107], v126 offset:0
	v_mfma_f32_32x32x16_bf16 v[16:31], v[68:71], v[72:75], v[16:31]
	ds_read_b128 v[108:111], v126 offset:4096
	v_mfma_f32_32x32x16_bf16 v[0:15], v[68:71], v[76:79], v[0:15]
	ds_read_b128 v[100:103], v122 offset:4096
	s_waitcnt lgkmcnt(4)
	v_mfma_f32_32x32x16_bf16 v[48:63], v[80:83], v[88:91], v[48:63]
	ds_read_b128 v[64:67], v123 offset:0
	v_mfma_f32_32x32x16_bf16 v[32:47], v[80:83], v[92:95], v[32:47]
	ds_read_b128 v[72:75], v127 offset:0
	v_mfma_f32_32x32x16_bf16 v[16:31], v[84:87], v[88:91], v[16:31]
	ds_read_b128 v[76:79], v127 offset:4096
	v_mfma_f32_32x32x16_bf16 v[0:15], v[84:87], v[92:95], v[0:15]
	ds_read_b128 v[68:71], v123 offset:4096
	s_waitcnt lgkmcnt(4)
	v_mfma_f32_32x32x16_bf16 v[48:63], v[96:99], v[104:107], v[48:63]
	v_mfma_f32_32x32x16_bf16 v[32:47], v[96:99], v[108:111], v[32:47]
	v_mfma_f32_32x32x16_bf16 v[16:31], v[100:103], v[104:107], v[16:31]
	v_mfma_f32_32x32x16_bf16 v[0:15], v[100:103], v[108:111], v[0:15]
	s_waitcnt lgkmcnt(0)
	v_mfma_f32_32x32x16_bf16 v[48:63], v[64:67], v[72:75], v[48:63]
	v_mfma_f32_32x32x16_bf16 v[32:47], v[64:67], v[76:79], v[32:47]
	v_mfma_f32_32x32x16_bf16 v[16:31], v[68:71], v[72:75], v[16:31]
	v_mfma_f32_32x32x16_bf16 v[0:15], v[68:71], v[76:79], v[0:15]
	s_barrier
	s_waitcnt vmcnt(0)
	s_barrier
	ds_read_b128 v[64:67], v120 offset:32768
	ds_read_b128 v[72:75], v124 offset:32768
	ds_read_b128 v[76:79], v124 offset:36864
	ds_read_b128 v[68:71], v120 offset:36864
	ds_read_b128 v[80:83], v121 offset:32768
	ds_read_b128 v[88:91], v125 offset:32768
	ds_read_b128 v[92:95], v125 offset:36864
	ds_read_b128 v[84:87], v121 offset:36864
	s_waitcnt lgkmcnt(4)
	v_mfma_f32_32x32x16_bf16 v[48:63], v[64:67], v[72:75], v[48:63]
	ds_read_b128 v[96:99], v122 offset:32768
	v_mfma_f32_32x32x16_bf16 v[32:47], v[64:67], v[76:79], v[32:47]
	ds_read_b128 v[104:107], v126 offset:32768
	v_mfma_f32_32x32x16_bf16 v[16:31], v[68:71], v[72:75], v[16:31]
	ds_read_b128 v[108:111], v126 offset:36864
	v_mfma_f32_32x32x16_bf16 v[0:15], v[68:71], v[76:79], v[0:15]
	ds_read_b128 v[100:103], v122 offset:36864
	s_waitcnt lgkmcnt(4)
	v_mfma_f32_32x32x16_bf16 v[48:63], v[80:83], v[88:91], v[48:63]
	ds_read_b128 v[64:67], v123 offset:32768
	v_mfma_f32_32x32x16_bf16 v[32:47], v[80:83], v[92:95], v[32:47]
	ds_read_b128 v[72:75], v127 offset:32768
	v_mfma_f32_32x32x16_bf16 v[16:31], v[84:87], v[88:91], v[16:31]
	ds_read_b128 v[76:79], v127 offset:36864
	v_mfma_f32_32x32x16_bf16 v[0:15], v[84:87], v[92:95], v[0:15]
	ds_read_b128 v[68:71], v123 offset:36864
	s_waitcnt lgkmcnt(4)
	v_mfma_f32_32x32x16_bf16 v[48:63], v[96:99], v[104:107], v[48:63]
	v_mfma_f32_32x32x16_bf16 v[32:47], v[96:99], v[108:111], v[32:47]
	v_mfma_f32_32x32x16_bf16 v[16:31], v[100:103], v[104:107], v[16:31]
	v_mfma_f32_32x32x16_bf16 v[0:15], v[100:103], v[108:111], v[0:15]
	s_waitcnt lgkmcnt(0)
	v_mfma_f32_32x32x16_bf16 v[48:63], v[64:67], v[72:75], v[48:63]
	v_mfma_f32_32x32x16_bf16 v[32:47], v[64:67], v[76:79], v[32:47]
	v_mfma_f32_32x32x16_bf16 v[16:31], v[68:71], v[72:75], v[16:31]
	v_mfma_f32_32x32x16_bf16 v[0:15], v[68:71], v[76:79], v[0:15]
	s_nop 7
	s_nop 7
	s_branch .LBB0_1034

.LBB0_1103:
	ds_read_b128 v[164:167], v185
	ds_read_b128 v[172:175], v185 offset:4608
	ds_read_b128 v[168:171], v187 offset:36864
	ds_read_b128 v[176:179], v187 offset:41472
	s_add_i32 s12, s12, 3
	s_cmp_ge_u32 s12, s8
	s_waitcnt lgkmcnt(1)
	v_mfma_f32_32x32x16_bf16 v[48:63], v[164:167], v[168:171], v[48:63]
	ds_read_b128 v[202:205], v185 offset:32
	s_waitcnt lgkmcnt(1)
	v_mfma_f32_32x32x16_bf16 v[16:31], v[164:167], v[176:179], v[16:31]
	ds_read_b128 v[164:167], v187 offset:36896
	v_mfma_f32_32x32x16_bf16 v[32:47], v[172:175], v[168:171], v[32:47]
	ds_read_b128 v[168:171], v185 offset:4640
	v_mfma_f32_32x32x16_bf16 v[0:15], v[172:175], v[176:179], v[0:15]
	ds_read_b128 v[172:175], v187 offset:41504
	s_waitcnt lgkmcnt(2)
	v_mfma_f32_32x32x16_bf16 v[48:63], v[202:205], v[164:167], v[48:63]
	ds_read_b128 v[176:179], v185 offset:64
	s_waitcnt lgkmcnt(1)
	v_mfma_f32_32x32x16_bf16 v[16:31], v[202:205], v[172:175], v[16:31]
	ds_read_b128 v[202:205], v185 offset:4672
	v_mfma_f32_32x32x16_bf16 v[32:47], v[168:171], v[164:167], v[32:47]
	ds_read_b128 v[164:167], v187 offset:36928
	v_mfma_f32_32x32x16_bf16 v[0:15], v[168:171], v[172:175], v[0:15]
	ds_read_b128 v[168:171], v187 offset:41536
	s_waitcnt lgkmcnt(1)
	v_mfma_f32_32x32x16_bf16 v[48:63], v[176:179], v[164:167], v[48:63]
	ds_read_b128 v[172:175], v185 offset:96
	s_waitcnt lgkmcnt(1)
	v_mfma_f32_32x32x16_bf16 v[16:31], v[176:179], v[168:171], v[16:31]
	ds_read_b128 v[176:179], v185 offset:4704
	v_mfma_f32_32x32x16_bf16 v[32:47], v[202:205], v[164:167], v[32:47]
	ds_read_b128 v[164:167], v187 offset:36960
	v_mfma_f32_32x32x16_bf16 v[0:15], v[202:205], v[168:171], v[0:15]
	ds_read_b128 v[168:171], v187 offset:41568
	s_waitcnt lgkmcnt(1)
	v_mfma_f32_32x32x16_bf16 v[48:63], v[172:175], v[164:167], v[48:63]
	s_cbranch_scc1 .Lgw3_last
	s_waitcnt vmcnt(8)
	s_branch .Lgw3_go

.Lgw3_go:
	ds_write_b128 v188, v[88:91] offset:18432
	s_waitcnt lgkmcnt(1)
	v_mfma_f32_32x32x16_bf16 v[16:31], v[172:175], v[168:171], v[16:31]
	ds_write_b128 v188, v[92:95] offset:23040
	v_mfma_f32_32x32x16_bf16 v[32:47], v[176:179], v[164:167], v[32:47]
	ds_write_b128 v188, v[104:107] offset:27648
	v_mfma_f32_32x32x16_bf16 v[0:15], v[176:179], v[168:171], v[0:15]
	ds_write_b128 v188, v[108:111] offset:32256
	ds_write_b128 v188, v[112:115] offset:55296
	ds_write_b128 v188, v[116:119] offset:59904
	ds_write_b128 v188, v[120:123] offset:64512
	ds_write_b128 v189, v[124:127] offset:13824
	s_waitcnt lgkmcnt(0)
	s_barrier
	s_cbranch_scc1 .LBB0_1105
	v_add_co_u32_e32 v88, vcc, 0x3971000, v146
	s_nop 1
	v_addc_co_u32_e32 v89, vcc, 0, v147, vcc
	v_add_co_u32_e32 v92, vcc, 0x399d000, v146
	s_nop 1
	v_addc_co_u32_e32 v93, vcc, 0, v147, vcc
	v_add_co_u32_e32 v104, vcc, 0x39c9000, v146
	global_load_dwordx4 v[88:91], v[88:89], off offset:2688
	s_nop 0
	global_load_dwordx4 v[92:95], v[92:93], off offset:2688
	v_addc_co_u32_e32 v105, vcc, 0, v147, vcc
	v_add_co_u32_e32 v108, vcc, 0x39f5000, v146
	s_nop 1
	v_addc_co_u32_e32 v109, vcc, 0, v147, vcc
	v_add_co_u32_e32 v112, vcc, 0x2140000, v144
	global_load_dwordx4 v[104:107], v[104:105], off offset:2688
	s_nop 0
	global_load_dwordx4 v[108:111], v[108:109], off offset:2688
	v_addc_co_u32_e32 v113, vcc, 0, v145, vcc
	v_add_co_u32_e32 v116, vcc, 0x216c000, v144
	s_nop 1
	v_addc_co_u32_e32 v117, vcc, 0, v145, vcc
	v_add_co_u32_e32 v120, vcc, 0x2198000, v144
	global_load_dwordx4 v[112:115], v[112:113], off offset:384
	s_nop 0
	global_load_dwordx4 v[116:119], v[116:117], off offset:384
	v_addc_co_u32_e32 v121, vcc, 0, v145, vcc
	v_add_co_u32_e32 v124, vcc, 0x21c4000, v144
	s_nop 1
	v_addc_co_u32_e32 v125, vcc, 0, v145, vcc
	global_load_dwordx4 v[120:123], v[120:121], off offset:384
	s_nop 0
	global_load_dwordx4 v[124:127], v[124:125], off offset:384
.LBB0_1105:
	ds_read_b128 v[144:147], v185 offset:18432
	ds_read_b128 v[168:171], v185 offset:23040
	ds_read_b128 v[164:167], v187 offset:55296
	ds_read_b128 v[172:175], v187 offset:59904
	s_andn2_b64 vcc, exec, s[6:7]
	s_waitcnt lgkmcnt(1)
	v_mfma_f32_32x32x16_bf16 v[48:63], v[144:147], v[164:167], v[48:63]
	ds_read_b128 v[176:179], v185 offset:18464
	s_waitcnt lgkmcnt(1)
	v_mfma_f32_32x32x16_bf16 v[16:31], v[144:147], v[172:175], v[16:31]
	ds_read_b128 v[144:147], v187 offset:55328
	v_mfma_f32_32x32x16_bf16 v[32:47], v[168:171], v[164:167], v[32:47]
	ds_read_b128 v[164:167], v185 offset:23072
	v_mfma_f32_32x32x16_bf16 v[0:15], v[168:171], v[172:175], v[0:15]
	ds_read_b128 v[168:171], v187 offset:59936
	s_waitcnt lgkmcnt(2)
	v_mfma_f32_32x32x16_bf16 v[48:63], v[176:179], v[144:147], v[48:63]
	ds_read_b128 v[172:175], v185 offset:18496
	s_waitcnt lgkmcnt(1)
	v_mfma_f32_32x32x16_bf16 v[16:31], v[176:179], v[168:171], v[16:31]
	ds_read_b128 v[176:179], v185 offset:23104
	v_mfma_f32_32x32x16_bf16 v[32:47], v[164:167], v[144:147], v[32:47]
	ds_read_b128 v[144:147], v187 offset:55360
	v_mfma_f32_32x32x16_bf16 v[0:15], v[164:167], v[168:171], v[0:15]
	ds_read_b128 v[164:167], v187 offset:59968
	s_waitcnt lgkmcnt(1)
	v_mfma_f32_32x32x16_bf16 v[48:63], v[172:175], v[144:147], v[48:63]
	ds_read_b128 v[168:171], v185 offset:18528
	s_waitcnt lgkmcnt(1)
	v_mfma_f32_32x32x16_bf16 v[16:31], v[172:175], v[164:167], v[16:31]
	ds_read_b128 v[172:175], v185 offset:23136
	v_mfma_f32_32x32x16_bf16 v[32:47], v[176:179], v[144:147], v[32:47]
	ds_read_b128 v[144:147], v187 offset:55392
	v_mfma_f32_32x32x16_bf16 v[0:15], v[176:179], v[164:167], v[0:15]
	ds_read_b128 v[164:167], v187 offset:60000
	s_waitcnt lgkmcnt(1)
	v_mfma_f32_32x32x16_bf16 v[48:63], v[168:171], v[144:147], v[48:63]
	s_waitcnt lgkmcnt(0)
	v_mfma_f32_32x32x16_bf16 v[16:31], v[168:171], v[164:167], v[16:31]
	v_mfma_f32_32x32x16_bf16 v[32:47], v[172:175], v[144:147], v[32:47]
	v_mfma_f32_32x32x16_bf16 v[0:15], v[172:175], v[164:167], v[0:15]
	s_cbranch_vccnz .LBB0_1100
	s_waitcnt vmcnt(8)
	ds_write_b128 v188, v[64:67]
	ds_write_b128 v188, v[68:71] offset:4608
	ds_write_b128 v188, v[72:75] offset:9216
	ds_write_b128 v188, v[80:83] offset:13824
	ds_write_b128 v188, v[76:79] offset:36864
	ds_write_b128 v188, v[84:87] offset:41472
	ds_write_b128 v188, v[96:99] offset:46080
	ds_write_b128 v188, v[100:103] offset:50688
	s_branch .LBB0_1100

.LBB0_1510:
	s_mul_hi_i32 s6, s74, 0x2aaaaaab
	s_lshr_b32 s7, s6, 31
	s_ashr_i32 s6, s6, 4
	s_add_i32 s6, s6, s7
	s_mul_i32 s7, s6, 0x60
	s_sub_i32 s7, s74, s7
	s_lshl_b32 s11, s7, 7
	s_lshl_b32 s10, s6, 7
	v_lshl_or_b32 v64, v183, 3, v191
	v_and_b32_e32 v65, 63, v64
	v_lshrrev_b32_e32 v66, 3, v65
	v_lshrrev_b32_e32 v67, 4, v65
	v_xor_b32_e32 v67, v67, v65
	v_and_b32_e32 v67, 7, v67
	v_lshlrev_b32_e32 v67, 4, v67
	s_movk_i32 s99, 0x800
	v_mad_u32_u24 v112, v66, s99, v67
	v_xor_b32_e32 v68, 64, v112
	v_add_u32_e32 v113, 0x3c00, v68
	v_add_u32_e32 v114, 0x7800, v112
	v_add_u32_e32 v115, 0xb400, v68
	v_add_u32_e32 v116, 0x10000, v112
	v_add_u32_e32 v117, 0x13c00, v68
	v_add_u32_e32 v118, 0x17800, v112
	v_add_u32_e32 v119, 0x1b400, v68
	v_and_b32_e32 v69, 31, v64
	v_bfe_u32 v70, v64, 5, 1
	v_bfe_u32 v71, v64, 1, 3
	v_xor_b32_e32 v71, v71, v70
	v_lshlrev_b32_e32 v71, 4, v71
	v_bfe_u32 v72, v64, 7, 1
	v_lshl_or_b32 v72, v72, 6, v69
	v_lshl_add_u32 v120, v72, 7, v71
	v_bfe_u32 v73, v64, 6, 1
	v_lshl_or_b32 v73, v73, 6, v69
	v_lshl_add_u32 v124, v73, 7, v71
	v_add_u32_e32 v124, 0x4000, v124
	v_xor_b32_e32 v121, 32, v120
	v_xor_b32_e32 v125, 32, v124
	v_xor_b32_e32 v122, 64, v120
	v_xor_b32_e32 v126, 64, v124
	v_xor_b32_e32 v123, 96, v120
	v_xor_b32_e32 v127, 96, v124
	v_lshrrev_b32_e32 v74, 6, v64
	s_nop 0
	v_readfirstlane_b32 s100, v74
	s_nop 3
	s_lshl_b32 s98, s100, 13
	s_mov_b32 s101, 0x2c40000
	s_mov_b32 s99, s10
	s_cmp_lt_u32 s100, 2
	s_cmov_b32 s101, 0xb171900
	s_cmov_b32 s99, s11
	s_and_b32 s100, s100, 1
	s_lshl_b32 s100, s100, 6
	s_add_u32 s99, s99, s100
	s_mul_i32 s99, s99, 0x800
	s_add_u32 s99, s99, s101
	s_add_u32 s6, s90, s99
	s_addc_u32 s7, s91, 0
	s_add_u32 m0, s98, 0x0
	s_nop 0
	global_load_lds_dwordx4 v112, s[6:7] offset:0
	global_load_lds_dwordx4 v113, s[6:7] offset:1024
	global_load_lds_dwordx4 v114, s[6:7] offset:2048
	global_load_lds_dwordx4 v115, s[6:7] offset:3072
	s_add_u32 m0, s98, 0x1000
	s_nop 0
	global_load_lds_dwordx4 v116, s[6:7] offset:0
	global_load_lds_dwordx4 v117, s[6:7] offset:1024
	global_load_lds_dwordx4 v118, s[6:7] offset:2048
	global_load_lds_dwordx4 v119, s[6:7] offset:3072
	s_add_u32 s6, s6, 0x80
	s_addc_u32 s7, s7, 0
	s_add_u32 m0, s98, 0x8000
	s_nop 0
	global_load_lds_dwordx4 v112, s[6:7] offset:0
	global_load_lds_dwordx4 v113, s[6:7] offset:1024
	global_load_lds_dwordx4 v114, s[6:7] offset:2048
	global_load_lds_dwordx4 v115, s[6:7] offset:3072
	s_add_u32 m0, s98, 0x9000
	s_nop 0
	global_load_lds_dwordx4 v116, s[6:7] offset:0
	global_load_lds_dwordx4 v117, s[6:7] offset:1024
	global_load_lds_dwordx4 v118, s[6:7] offset:2048
	global_load_lds_dwordx4 v119, s[6:7] offset:3072
	s_add_u32 s6, s6, 0x80
	s_addc_u32 s7, s7, 0
	v_mov_b32_e32 v48, 0
	v_mov_b32_e32 v49, 0
	v_mov_b32_e32 v50, 0
	v_mov_b32_e32 v51, 0
	v_mov_b32_e32 v52, 0
	v_mov_b32_e32 v53, 0
	v_mov_b32_e32 v54, 0
	v_mov_b32_e32 v55, 0
	v_mov_b32_e32 v56, 0
	v_mov_b32_e32 v57, 0
	v_mov_b32_e32 v58, 0
	v_mov_b32_e32 v59, 0
	v_mov_b32_e32 v60, 0
	v_mov_b32_e32 v61, 0
	v_mov_b32_e32 v62, 0
	v_mov_b32_e32 v63, 0
	v_mov_b32_e32 v16, 0
	v_mov_b32_e32 v17, 0
	v_mov_b32_e32 v18, 0
	v_mov_b32_e32 v19, 0
	v_mov_b32_e32 v20, 0
	v_mov_b32_e32 v21, 0
	v_mov_b32_e32 v22, 0
	v_mov_b32_e32 v23, 0
	v_mov_b32_e32 v24, 0
	v_mov_b32_e32 v25, 0
	v_mov_b32_e32 v26, 0
	v_mov_b32_e32 v27, 0
	v_mov_b32_e32 v28, 0
	v_mov_b32_e32 v29, 0
	v_mov_b32_e32 v30, 0
	v_mov_b32_e32 v31, 0
	v_mov_b32_e32 v32, 0
	v_mov_b32_e32 v33, 0
	v_mov_b32_e32 v34, 0
	v_mov_b32_e32 v35, 0
	v_mov_b32_e32 v36, 0
	v_mov_b32_e32 v37, 0
	v_mov_b32_e32 v38, 0
	v_mov_b32_e32 v39, 0
	v_mov_b32_e32 v40, 0
	v_mov_b32_e32 v41, 0
	v_mov_b32_e32 v42, 0
	v_mov_b32_e32 v43, 0
	v_mov_b32_e32 v44, 0
	v_mov_b32_e32 v45, 0
	v_mov_b32_e32 v46, 0
	v_mov_b32_e32 v47, 0
	v_mov_b32_e32 v0, 0
	v_mov_b32_e32 v1, 0
	v_mov_b32_e32 v2, 0
	v_mov_b32_e32 v3, 0
	v_mov_b32_e32 v4, 0
	v_mov_b32_e32 v5, 0
	v_mov_b32_e32 v6, 0
	v_mov_b32_e32 v7, 0
	v_mov_b32_e32 v8, 0
	v_mov_b32_e32 v9, 0
	v_mov_b32_e32 v10, 0
	v_mov_b32_e32 v11, 0
	v_mov_b32_e32 v12, 0
	v_mov_b32_e32 v13, 0
	v_mov_b32_e32 v14, 0
	v_mov_b32_e32 v15, 0
	s_movk_i32 s8, 7
	s_waitcnt vmcnt(8)
.Lg4_loop:
	s_waitcnt vmcnt(8)
	s_barrier
	ds_read_b128 v[64:67], v120 offset:0
	ds_read_b128 v[72:75], v124 offset:0
	ds_read_b128 v[76:79], v124 offset:4096
	ds_read_b128 v[68:71], v120 offset:4096
	ds_read_b128 v[80:83], v121 offset:0
	ds_read_b128 v[88:91], v125 offset:0
	ds_read_b128 v[92:95], v125 offset:4096
	ds_read_b128 v[84:87], v121 offset:4096
	s_waitcnt lgkmcnt(4)
	v_mfma_f32_32x32x16_bf16 v[48:63], v[64:67], v[72:75], v[48:63]
	ds_read_b128 v[96:99], v122 offset:0
	v_mfma_f32_32x32x16_bf16 v[16:31], v[64:67], v[76:79], v[16:31]
	ds_read_b128 v[104:107], v126 offset:0
	v_mfma_f32_32x32x16_bf16 v[32:47], v[68:71], v[72:75], v[32:47]
	ds_read_b128 v[108:111], v126 offset:4096
	v_mfma_f32_32x32x16_bf16 v[0:15], v[68:71], v[76:79], v[0:15]
	ds_read_b128 v[100:103], v122 offset:4096
	s_waitcnt lgkmcnt(4)
	v_mfma_f32_32x32x16_bf16 v[48:63], v[80:83], v[88:91], v[48:63]
	ds_read_b128 v[64:67], v123 offset:0
	v_mfma_f32_32x32x16_bf16 v[16:31], v[80:83], v[92:95], v[16:31]
	ds_read_b128 v[72:75], v127 offset:0
	v_mfma_f32_32x32x16_bf16 v[32:47], v[84:87], v[88:91], v[32:47]
	ds_read_b128 v[76:79], v127 offset:4096
	v_mfma_f32_32x32x16_bf16 v[0:15], v[84:87], v[92:95], v[0:15]
	ds_read_b128 v[68:71], v123 offset:4096
	s_waitcnt lgkmcnt(4)
	v_mfma_f32_32x32x16_bf16 v[48:63], v[96:99], v[104:107], v[48:63]
	v_mfma_f32_32x32x16_bf16 v[16:31], v[96:99], v[108:111], v[16:31]
	v_mfma_f32_32x32x16_bf16 v[32:47], v[100:103], v[104:107], v[32:47]
	v_mfma_f32_32x32x16_bf16 v[0:15], v[100:103], v[108:111], v[0:15]
	s_waitcnt lgkmcnt(0)
	v_mfma_f32_32x32x16_bf16 v[48:63], v[64:67], v[72:75], v[48:63]
	v_mfma_f32_32x32x16_bf16 v[16:31], v[64:67], v[76:79], v[16:31]
	v_mfma_f32_32x32x16_bf16 v[32:47], v[68:71], v[72:75], v[32:47]
	v_mfma_f32_32x32x16_bf16 v[0:15], v[68:71], v[76:79], v[0:15]
	s_barrier
	s_add_u32 m0, s98, 0x0
	s_nop 0
	global_load_lds_dwordx4 v112, s[6:7] offset:0
	global_load_lds_dwordx4 v113, s[6:7] offset:1024
	global_load_lds_dwordx4 v114, s[6:7] offset:2048
	global_load_lds_dwordx4 v115, s[6:7] offset:3072
	s_add_u32 m0, s98, 0x1000
	s_nop 0
	global_load_lds_dwordx4 v116, s[6:7] offset:0
	global_load_lds_dwordx4 v117, s[6:7] offset:1024
	global_load_lds_dwordx4 v118, s[6:7] offset:2048
	global_load_lds_dwordx4 v119, s[6:7] offset:3072
	s_add_u32 s6, s6, 0x80
	s_addc_u32 s7, s7, 0
	s_waitcnt vmcnt(8)
	s_barrier
	ds_read_b128 v[64:67], v120 offset:32768
	ds_read_b128 v[72:75], v124 offset:32768
	ds_read_b128 v[76:79], v124 offset:36864
	ds_read_b128 v[68:71], v120 offset:36864
	ds_read_b128 v[80:83], v121 offset:32768
	ds_read_b128 v[88:91], v125 offset:32768
	ds_read_b128 v[92:95], v125 offset:36864
	ds_read_b128 v[84:87], v121 offset:36864
	s_waitcnt lgkmcnt(4)
	v_mfma_f32_32x32x16_bf16 v[48:63], v[64:67], v[72:75], v[48:63]
	ds_read_b128 v[96:99], v122 offset:32768
	v_mfma_f32_32x32x16_bf16 v[16:31], v[64:67], v[76:79], v[16:31]
	ds_read_b128 v[104:107], v126 offset:32768
	v_mfma_f32_32x32x16_bf16 v[32:47], v[68:71], v[72:75], v[32:47]
	ds_read_b128 v[108:111], v126 offset:36864
	v_mfma_f32_32x32x16_bf16 v[0:15], v[68:71], v[76:79], v[0:15]
	ds_read_b128 v[100:103], v122 offset:36864
	s_waitcnt lgkmcnt(4)
	v_mfma_f32_32x32x16_bf16 v[48:63], v[80:83], v[88:91], v[48:63]
	ds_read_b128 v[64:67], v123 offset:32768
	v_mfma_f32_32x32x16_bf16 v[16:31], v[80:83], v[92:95], v[16:31]
	ds_read_b128 v[72:75], v127 offset:32768
	v_mfma_f32_32x32x16_bf16 v[32:47], v[84:87], v[88:91], v[32:47]
	ds_read_b128 v[76:79], v127 offset:36864
	v_mfma_f32_32x32x16_bf16 v[0:15], v[84:87], v[92:95], v[0:15]
	ds_read_b128 v[68:71], v123 offset:36864
	s_waitcnt lgkmcnt(4)
	v_mfma_f32_32x32x16_bf16 v[48:63], v[96:99], v[104:107], v[48:63]
	v_mfma_f32_32x32x16_bf16 v[16:31], v[96:99], v[108:111], v[16:31]
	v_mfma_f32_32x32x16_bf16 v[32:47], v[100:103], v[104:107], v[32:47]
	v_mfma_f32_32x32x16_bf16 v[0:15], v[100:103], v[108:111], v[0:15]
	s_waitcnt lgkmcnt(0)
	v_mfma_f32_32x32x16_bf16 v[48:63], v[64:67], v[72:75], v[48:63]
	v_mfma_f32_32x32x16_bf16 v[16:31], v[64:67], v[76:79], v[16:31]
	v_mfma_f32_32x32x16_bf16 v[32:47], v[68:71], v[72:75], v[32:47]
	v_mfma_f32_32x32x16_bf16 v[0:15], v[68:71], v[76:79], v[0:15]
	s_barrier
	s_add_u32 m0, s98, 0x8000
	s_nop 0
	global_load_lds_dwordx4 v112, s[6:7] offset:0
	global_load_lds_dwordx4 v113, s[6:7] offset:1024
	global_load_lds_dwordx4 v114, s[6:7] offset:2048
	global_load_lds_dwordx4 v115, s[6:7] offset:3072
	s_add_u32 m0, s98, 0x9000
	s_nop 0
	global_load_lds_dwordx4 v116, s[6:7] offset:0
	global_load_lds_dwordx4 v117, s[6:7] offset:1024
	global_load_lds_dwordx4 v118, s[6:7] offset:2048
	global_load_lds_dwordx4 v119, s[6:7] offset:3072
	s_add_u32 s6, s6, 0x80
	s_addc_u32 s7, s7, 0
	s_sub_u32 s8, s8, 1
	s_cmp_lg_u32 s8, 0
	s_cbranch_scc1 .Lg4_loop
	s_waitcnt vmcnt(8)
	s_barrier
	ds_read_b128 v[64:67], v120 offset:0
	ds_read_b128 v[72:75], v124 offset:0
	ds_read_b128 v[76:79], v124 offset:4096
	ds_read_b128 v[68:71], v120 offset:4096
	ds_read_b128 v[80:83], v121 offset:0
	ds_read_b128 v[88:91], v125 offset:0
	ds_read_b128 v[92:95], v125 offset:4096
	ds_read_b128 v[84:87], v121 offset:4096
	s_waitcnt lgkmcnt(4)
	v_mfma_f32_32x32x16_bf16 v[48:63], v[64:67], v[72:75], v[48:63]
	ds_read_b128 v[96:99], v122 offset:0
	v_mfma_f32_32x32x16_bf16 v[16:31], v[64:67], v[76:79], v[16:31]
	ds_read_b128 v[104:107], v126 offset:0
	v_mfma_f32_32x32x16_bf16 v[32:47], v[68:71], v[72:75], v[32:47]
	ds_read_b128 v[108:111], v126 offset:4096
	v_mfma_f32_32x32x16_bf16 v[0:15], v[68:71], v[76:79], v[0:15]
	ds_read_b128 v[100:103], v122 offset:4096
	s_waitcnt lgkmcnt(4)
	v_mfma_f32_32x32x16_bf16 v[48:63], v[80:83], v[88:91], v[48:63]
	ds_read_b128 v[64:67], v123 offset:0
	v_mfma_f32_32x32x16_bf16 v[16:31], v[80:83], v[92:95], v[16:31]
	ds_read_b128 v[72:75], v127 offset:0
	v_mfma_f32_32x32x16_bf16 v[32:47], v[84:87], v[88:91], v[32:47]
	ds_read_b128 v[76:79], v127 offset:4096
	v_mfma_f32_32x32x16_bf16 v[0:15], v[84:87], v[92:95], v[0:15]
	ds_read_b128 v[68:71], v123 offset:4096
	s_waitcnt lgkmcnt(4)
	v_mfma_f32_32x32x16_bf16 v[48:63], v[96:99], v[104:107], v[48:63]
	v_mfma_f32_32x32x16_bf16 v[16:31], v[96:99], v[108:111], v[16:31]
	v_mfma_f32_32x32x16_bf16 v[32:47], v[100:103], v[104:107], v[32:47]
	v_mfma_f32_32x32x16_bf16 v[0:15], v[100:103], v[108:111], v[0:15]
	s_waitcnt lgkmcnt(0)
	v_mfma_f32_32x32x16_bf16 v[48:63], v[64:67], v[72:75], v[48:63]
	v_mfma_f32_32x32x16_bf16 v[16:31], v[64:67], v[76:79], v[16:31]
	v_mfma_f32_32x32x16_bf16 v[32:47], v[68:71], v[72:75], v[32:47]
	v_mfma_f32_32x32x16_bf16 v[0:15], v[68:71], v[76:79], v[0:15]
	s_barrier
	s_waitcnt vmcnt(0)
	s_barrier
	ds_read_b128 v[64:67], v120 offset:32768
	ds_read_b128 v[72:75], v124 offset:32768
	ds_read_b128 v[76:79], v124 offset:36864
	ds_read_b128 v[68:71], v120 offset:36864
	ds_read_b128 v[80:83], v121 offset:32768
	ds_read_b128 v[88:91], v125 offset:32768
	ds_read_b128 v[92:95], v125 offset:36864
	ds_read_b128 v[84:87], v121 offset:36864
	s_waitcnt lgkmcnt(4)
	v_mfma_f32_32x32x16_bf16 v[48:63], v[64:67], v[72:75], v[48:63]
	ds_read_b128 v[96:99], v122 offset:32768
	v_mfma_f32_32x32x16_bf16 v[16:31], v[64:67], v[76:79], v[16:31]
	ds_read_b128 v[104:107], v126 offset:32768
	v_mfma_f32_32x32x16_bf16 v[32:47], v[68:71], v[72:75], v[32:47]
	ds_read_b128 v[108:111], v126 offset:36864
	v_mfma_f32_32x32x16_bf16 v[0:15], v[68:71], v[76:79], v[0:15]
	ds_read_b128 v[100:103], v122 offset:36864
	s_waitcnt lgkmcnt(4)
	v_mfma_f32_32x32x16_bf16 v[48:63], v[80:83], v[88:91], v[48:63]
	ds_read_b128 v[64:67], v123 offset:32768
	v_mfma_f32_32x32x16_bf16 v[16:31], v[80:83], v[92:95], v[16:31]
	ds_read_b128 v[72:75], v127 offset:32768
	v_mfma_f32_32x32x16_bf16 v[32:47], v[84:87], v[88:91], v[32:47]
	ds_read_b128 v[76:79], v127 offset:36864
	v_mfma_f32_32x32x16_bf16 v[0:15], v[84:87], v[92:95], v[0:15]
	ds_read_b128 v[68:71], v123 offset:36864
	s_waitcnt lgkmcnt(4)
	v_mfma_f32_32x32x16_bf16 v[48:63], v[96:99], v[104:107], v[48:63]
	v_mfma_f32_32x32x16_bf16 v[16:31], v[96:99], v[108:111], v[16:31]
	v_mfma_f32_32x32x16_bf16 v[32:47], v[100:103], v[104:107], v[32:47]
	v_mfma_f32_32x32x16_bf16 v[0:15], v[100:103], v[108:111], v[0:15]
	s_waitcnt lgkmcnt(0)
	v_mfma_f32_32x32x16_bf16 v[48:63], v[64:67], v[72:75], v[48:63]
	v_mfma_f32_32x32x16_bf16 v[16:31], v[64:67], v[76:79], v[16:31]
	v_mfma_f32_32x32x16_bf16 v[32:47], v[68:71], v[72:75], v[32:47]
	v_mfma_f32_32x32x16_bf16 v[0:15], v[68:71], v[76:79], v[0:15]
	s_nop 7
	s_nop 7
	s_branch .LBB0_1518

.LBB0_1878:
	ds_read_b128 v[144:147], v185
	ds_read_b128 v[158:161], v185 offset:4608
	ds_read_b128 v[154:157], v187 offset:36864
	ds_read_b128 v[162:165], v187 offset:41472
	s_add_i32 s12, s12, 3
	s_cmp_ge_u32 s12, s8
	s_waitcnt lgkmcnt(1)
	v_mfma_f32_32x32x16_bf16 v[48:63], v[144:147], v[154:157], v[48:63]
	ds_read_b128 v[166:169], v185 offset:32
	s_waitcnt lgkmcnt(1)
	v_mfma_f32_32x32x16_bf16 v[16:31], v[144:147], v[162:165], v[16:31]
	ds_read_b128 v[144:147], v187 offset:36896
	v_mfma_f32_32x32x16_bf16 v[32:47], v[158:161], v[154:157], v[32:47]
	ds_read_b128 v[154:157], v185 offset:4640
	v_mfma_f32_32x32x16_bf16 v[0:15], v[158:161], v[162:165], v[0:15]
	ds_read_b128 v[158:161], v187 offset:41504
	s_waitcnt lgkmcnt(2)
	v_mfma_f32_32x32x16_bf16 v[48:63], v[166:169], v[144:147], v[48:63]
	ds_read_b128 v[162:165], v185 offset:64
	s_waitcnt lgkmcnt(1)
	v_mfma_f32_32x32x16_bf16 v[16:31], v[166:169], v[158:161], v[16:31]
	ds_read_b128 v[166:169], v185 offset:4672
	v_mfma_f32_32x32x16_bf16 v[32:47], v[154:157], v[144:147], v[32:47]
	ds_read_b128 v[144:147], v187 offset:36928
	v_mfma_f32_32x32x16_bf16 v[0:15], v[154:157], v[158:161], v[0:15]
	ds_read_b128 v[154:157], v187 offset:41536
	s_waitcnt lgkmcnt(1)
	v_mfma_f32_32x32x16_bf16 v[48:63], v[162:165], v[144:147], v[48:63]
	ds_read_b128 v[158:161], v185 offset:96
	s_waitcnt lgkmcnt(1)
	v_mfma_f32_32x32x16_bf16 v[16:31], v[162:165], v[154:157], v[16:31]
	ds_read_b128 v[162:165], v185 offset:4704
	v_mfma_f32_32x32x16_bf16 v[32:47], v[166:169], v[144:147], v[32:47]
	ds_read_b128 v[144:147], v187 offset:36960
	v_mfma_f32_32x32x16_bf16 v[0:15], v[166:169], v[154:157], v[0:15]
	ds_read_b128 v[154:157], v187 offset:41568
	s_waitcnt lgkmcnt(1)
	v_mfma_f32_32x32x16_bf16 v[48:63], v[158:161], v[144:147], v[48:63]
	s_cbranch_scc1 .Lgw5_last
	s_waitcnt vmcnt(8)
	s_branch .Lgw5_go

.Lgw5_go:
	ds_write_b128 v188, v[88:91] offset:18432
	s_waitcnt lgkmcnt(1)
	v_mfma_f32_32x32x16_bf16 v[16:31], v[158:161], v[154:157], v[16:31]
	ds_write_b128 v188, v[92:95] offset:23040
	v_mfma_f32_32x32x16_bf16 v[32:47], v[162:165], v[144:147], v[32:47]
	ds_write_b128 v188, v[104:107] offset:27648
	v_mfma_f32_32x32x16_bf16 v[0:15], v[162:165], v[154:157], v[0:15]
	ds_write_b128 v188, v[112:115] offset:32256
	ds_write_b128 v188, v[108:111] offset:55296
	ds_write_b128 v188, v[116:119] offset:59904
	ds_write_b128 v188, v[120:123] offset:64512
	ds_write_b128 v189, v[124:127] offset:13824
	s_waitcnt lgkmcnt(0)
	s_barrier
	s_cbranch_scc1 .LBB0_1880
	v_add_co_u32_e32 v88, vcc, 0xc971000, v142
	s_nop 1
	v_addc_co_u32_e32 v89, vcc, 0, v143, vcc
	v_add_co_u32_e32 v92, vcc, 0xc981000, v142
	s_nop 1
	v_addc_co_u32_e32 v93, vcc, 0, v143, vcc
	v_add_co_u32_e32 v104, vcc, 0xc991000, v142
	global_load_dwordx4 v[88:91], v[88:89], off offset:2688
	s_nop 0
	global_load_dwordx4 v[92:95], v[92:93], off offset:2688
	v_addc_co_u32_e32 v105, vcc, 0, v143, vcc
	v_add_co_u32_e32 v108, vcc, 0xc9a1000, v142
	s_nop 1
	v_addc_co_u32_e32 v109, vcc, 0, v143, vcc
	global_load_dwordx4 v[104:107], v[104:105], off offset:2688
	s_nop 0
	global_load_dwordx4 v[112:115], v[108:109], off offset:2688
	v_add_co_u32_e32 v108, vcc, 0x3240000, v140
	s_nop 1
	v_addc_co_u32_e32 v109, vcc, 0, v141, vcc
	v_add_co_u32_e32 v116, vcc, 0x3250000, v140
	s_nop 1
	v_addc_co_u32_e32 v117, vcc, 0, v141, vcc
	v_add_co_u32_e32 v120, vcc, 0x3260000, v140
	global_load_dwordx4 v[108:111], v[108:109], off offset:384
	s_nop 0
	global_load_dwordx4 v[116:119], v[116:117], off offset:384
	v_addc_co_u32_e32 v121, vcc, 0, v141, vcc
	v_add_co_u32_e32 v124, vcc, 0x3270000, v140
	s_nop 1
	v_addc_co_u32_e32 v125, vcc, 0, v141, vcc
	global_load_dwordx4 v[120:123], v[120:121], off offset:384
	s_nop 0
	global_load_dwordx4 v[124:127], v[124:125], off offset:384
.LBB0_1880:
	ds_read_b128 v[140:143], v185 offset:18432
	ds_read_b128 v[154:157], v185 offset:23040
	ds_read_b128 v[144:147], v187 offset:55296
	ds_read_b128 v[158:161], v187 offset:59904
	s_andn2_b64 vcc, exec, s[6:7]
	s_waitcnt lgkmcnt(1)
	v_mfma_f32_32x32x16_bf16 v[48:63], v[140:143], v[144:147], v[48:63]
	ds_read_b128 v[162:165], v185 offset:18464
	s_waitcnt lgkmcnt(1)
	v_mfma_f32_32x32x16_bf16 v[16:31], v[140:143], v[158:161], v[16:31]
	ds_read_b128 v[140:143], v187 offset:55328
	v_mfma_f32_32x32x16_bf16 v[32:47], v[154:157], v[144:147], v[32:47]
	ds_read_b128 v[144:147], v185 offset:23072
	v_mfma_f32_32x32x16_bf16 v[0:15], v[154:157], v[158:161], v[0:15]
	ds_read_b128 v[154:157], v187 offset:59936
	s_waitcnt lgkmcnt(2)
	v_mfma_f32_32x32x16_bf16 v[48:63], v[162:165], v[140:143], v[48:63]
	ds_read_b128 v[158:161], v185 offset:18496
	s_waitcnt lgkmcnt(1)
	v_mfma_f32_32x32x16_bf16 v[16:31], v[162:165], v[154:157], v[16:31]
	ds_read_b128 v[162:165], v185 offset:23104
	v_mfma_f32_32x32x16_bf16 v[32:47], v[144:147], v[140:143], v[32:47]
	ds_read_b128 v[140:143], v187 offset:55360
	v_mfma_f32_32x32x16_bf16 v[0:15], v[144:147], v[154:157], v[0:15]
	ds_read_b128 v[144:147], v187 offset:59968
	s_waitcnt lgkmcnt(1)
	v_mfma_f32_32x32x16_bf16 v[48:63], v[158:161], v[140:143], v[48:63]
	ds_read_b128 v[154:157], v185 offset:18528
	s_waitcnt lgkmcnt(1)
	v_mfma_f32_32x32x16_bf16 v[16:31], v[158:161], v[144:147], v[16:31]
	ds_read_b128 v[158:161], v185 offset:23136
	v_mfma_f32_32x32x16_bf16 v[32:47], v[162:165], v[140:143], v[32:47]
	ds_read_b128 v[140:143], v187 offset:55392
	v_mfma_f32_32x32x16_bf16 v[0:15], v[162:165], v[144:147], v[0:15]
	ds_read_b128 v[144:147], v187 offset:60000
	s_waitcnt lgkmcnt(1)
	v_mfma_f32_32x32x16_bf16 v[48:63], v[154:157], v[140:143], v[48:63]
	s_waitcnt lgkmcnt(0)
	v_mfma_f32_32x32x16_bf16 v[16:31], v[154:157], v[144:147], v[16:31]
	v_mfma_f32_32x32x16_bf16 v[32:47], v[158:161], v[140:143], v[32:47]
	v_mfma_f32_32x32x16_bf16 v[0:15], v[158:161], v[144:147], v[0:15]
	s_cbranch_vccnz .LBB0_1875
	s_waitcnt vmcnt(8)
	ds_write_b128 v188, v[64:67]
	ds_write_b128 v188, v[68:71] offset:4608
	ds_write_b128 v188, v[72:75] offset:9216
	ds_write_b128 v188, v[80:83] offset:13824
	ds_write_b128 v188, v[76:79] offset:36864
	ds_write_b128 v188, v[84:87] offset:41472
	ds_write_b128 v188, v[96:99] offset:46080
	ds_write_b128 v188, v[100:103] offset:50688
	s_branch .LBB0_1875

.LBB0_2284:
	s_mul_hi_i32 s4, s47, 0x2aaaaaab
	s_lshr_b32 s5, s4, 31
	s_ashr_i32 s4, s4, 4
	s_add_i32 s4, s4, s5
	s_mul_i32 s5, s4, 0x60
	s_sub_i32 s5, s47, s5
	s_lshl_b32 s48, s5, 7
	s_lshl_b32 s49, s4, 7
	v_lshl_or_b32 v64, v183, 3, v191
	v_and_b32_e32 v65, 63, v64
	v_lshrrev_b32_e32 v66, 3, v65
	v_lshrrev_b32_e32 v67, 4, v65
	v_xor_b32_e32 v67, v67, v65
	v_and_b32_e32 v67, 7, v67
	v_lshlrev_b32_e32 v67, 4, v67
	s_movk_i32 s99, 0x800
	v_mad_u32_u24 v112, v66, s99, v67
	v_xor_b32_e32 v68, 64, v112
	v_add_u32_e32 v113, 0x3c00, v68
	v_add_u32_e32 v114, 0x7800, v112
	v_add_u32_e32 v115, 0xb400, v68
	v_add_u32_e32 v116, 0x10000, v112
	v_add_u32_e32 v117, 0x13c00, v68
	v_add_u32_e32 v118, 0x17800, v112
	v_add_u32_e32 v119, 0x1b400, v68
	v_and_b32_e32 v69, 31, v64
	v_bfe_u32 v70, v64, 5, 1
	v_bfe_u32 v71, v64, 1, 3
	v_xor_b32_e32 v71, v71, v70
	v_lshlrev_b32_e32 v71, 4, v71
	v_bfe_u32 v72, v64, 7, 1
	v_lshl_or_b32 v72, v72, 6, v69
	v_lshl_add_u32 v120, v72, 7, v71
	v_bfe_u32 v73, v64, 6, 1
	v_lshl_or_b32 v73, v73, 6, v69
	v_lshl_add_u32 v124, v73, 7, v71
	v_add_u32_e32 v124, 0x4000, v124
	v_xor_b32_e32 v121, 32, v120
	v_xor_b32_e32 v125, 32, v124
	v_xor_b32_e32 v122, 64, v120
	v_xor_b32_e32 v126, 64, v124
	v_xor_b32_e32 v123, 96, v120
	v_xor_b32_e32 v127, 96, v124
	v_lshrrev_b32_e32 v74, 6, v64
	s_nop 0
	v_readfirstlane_b32 s100, v74
	s_nop 3
	s_lshl_b32 s98, s100, 13
	s_mov_b32 s101, 0x1640000
	s_mov_b32 s99, s49
	s_cmp_lt_u32 s100, 2
	s_cmov_b32 s101, 0xb171900
	s_cmov_b32 s99, s48
	s_and_b32 s100, s100, 1
	s_lshl_b32 s100, s100, 6
	s_add_u32 s99, s99, s100
	s_mul_i32 s99, s99, 0x800
	s_add_u32 s99, s99, s101
	s_add_u32 s4, s90, s99
	s_addc_u32 s5, s91, 0
	s_add_u32 m0, s98, 0x0
	s_nop 0
	global_load_lds_dwordx4 v112, s[4:5] offset:0
	global_load_lds_dwordx4 v113, s[4:5] offset:1024
	global_load_lds_dwordx4 v114, s[4:5] offset:2048
	global_load_lds_dwordx4 v115, s[4:5] offset:3072
	s_add_u32 m0, s98, 0x1000
	s_nop 0
	global_load_lds_dwordx4 v116, s[4:5] offset:0
	global_load_lds_dwordx4 v117, s[4:5] offset:1024
	global_load_lds_dwordx4 v118, s[4:5] offset:2048
	global_load_lds_dwordx4 v119, s[4:5] offset:3072
	s_add_u32 s4, s4, 0x80
	s_addc_u32 s5, s5, 0
	s_add_u32 m0, s98, 0x8000
	s_nop 0
	global_load_lds_dwordx4 v112, s[4:5] offset:0
	global_load_lds_dwordx4 v113, s[4:5] offset:1024
	global_load_lds_dwordx4 v114, s[4:5] offset:2048
	global_load_lds_dwordx4 v115, s[4:5] offset:3072
	s_add_u32 m0, s98, 0x9000
	s_nop 0
	global_load_lds_dwordx4 v116, s[4:5] offset:0
	global_load_lds_dwordx4 v117, s[4:5] offset:1024
	global_load_lds_dwordx4 v118, s[4:5] offset:2048
	global_load_lds_dwordx4 v119, s[4:5] offset:3072
	s_add_u32 s4, s4, 0x80
	s_addc_u32 s5, s5, 0
	v_mov_b32_e32 v48, 0
	v_mov_b32_e32 v49, 0
	v_mov_b32_e32 v50, 0
	v_mov_b32_e32 v51, 0
	v_mov_b32_e32 v52, 0
	v_mov_b32_e32 v53, 0
	v_mov_b32_e32 v54, 0
	v_mov_b32_e32 v55, 0
	v_mov_b32_e32 v56, 0
	v_mov_b32_e32 v57, 0
	v_mov_b32_e32 v58, 0
	v_mov_b32_e32 v59, 0
	v_mov_b32_e32 v60, 0
	v_mov_b32_e32 v61, 0
	v_mov_b32_e32 v62, 0
	v_mov_b32_e32 v63, 0
	v_mov_b32_e32 v32, 0
	v_mov_b32_e32 v33, 0
	v_mov_b32_e32 v34, 0
	v_mov_b32_e32 v35, 0
	v_mov_b32_e32 v36, 0
	v_mov_b32_e32 v37, 0
	v_mov_b32_e32 v38, 0
	v_mov_b32_e32 v39, 0
	v_mov_b32_e32 v40, 0
	v_mov_b32_e32 v41, 0
	v_mov_b32_e32 v42, 0
	v_mov_b32_e32 v43, 0
	v_mov_b32_e32 v44, 0
	v_mov_b32_e32 v45, 0
	v_mov_b32_e32 v46, 0
	v_mov_b32_e32 v47, 0
	v_mov_b32_e32 v16, 0
	v_mov_b32_e32 v17, 0
	v_mov_b32_e32 v18, 0
	v_mov_b32_e32 v19, 0
	v_mov_b32_e32 v20, 0
	v_mov_b32_e32 v21, 0
	v_mov_b32_e32 v22, 0
	v_mov_b32_e32 v23, 0
	v_mov_b32_e32 v24, 0
	v_mov_b32_e32 v25, 0
	v_mov_b32_e32 v26, 0
	v_mov_b32_e32 v27, 0
	v_mov_b32_e32 v28, 0
	v_mov_b32_e32 v29, 0
	v_mov_b32_e32 v30, 0
	v_mov_b32_e32 v31, 0
	v_mov_b32_e32 v0, 0
	v_mov_b32_e32 v1, 0
	v_mov_b32_e32 v2, 0
	v_mov_b32_e32 v3, 0
	v_mov_b32_e32 v4, 0
	v_mov_b32_e32 v5, 0
	v_mov_b32_e32 v6, 0
	v_mov_b32_e32 v7, 0
	v_mov_b32_e32 v8, 0
	v_mov_b32_e32 v9, 0
	v_mov_b32_e32 v10, 0
	v_mov_b32_e32 v11, 0
	v_mov_b32_e32 v12, 0
	v_mov_b32_e32 v13, 0
	v_mov_b32_e32 v14, 0
	v_mov_b32_e32 v15, 0
	s_movk_i32 s6, 7
	s_waitcnt vmcnt(8)
.Lg6_loop:
	s_waitcnt vmcnt(8)
	s_barrier
	ds_read_b128 v[64:67], v120 offset:0
	ds_read_b128 v[72:75], v124 offset:0
	ds_read_b128 v[76:79], v124 offset:4096
	ds_read_b128 v[68:71], v120 offset:4096
	ds_read_b128 v[80:83], v121 offset:0
	ds_read_b128 v[88:91], v125 offset:0
	ds_read_b128 v[92:95], v125 offset:4096
	ds_read_b128 v[84:87], v121 offset:4096
	s_waitcnt lgkmcnt(4)
	v_mfma_f32_32x32x16_bf16 v[48:63], v[64:67], v[72:75], v[48:63]
	ds_read_b128 v[96:99], v122 offset:0
	v_mfma_f32_32x32x16_bf16 v[32:47], v[64:67], v[76:79], v[32:47]
	ds_read_b128 v[104:107], v126 offset:0
	v_mfma_f32_32x32x16_bf16 v[16:31], v[68:71], v[72:75], v[16:31]
	ds_read_b128 v[108:111], v126 offset:4096
	v_mfma_f32_32x32x16_bf16 v[0:15], v[68:71], v[76:79], v[0:15]
	ds_read_b128 v[100:103], v122 offset:4096
	s_waitcnt lgkmcnt(4)
	v_mfma_f32_32x32x16_bf16 v[48:63], v[80:83], v[88:91], v[48:63]
	ds_read_b128 v[64:67], v123 offset:0
	v_mfma_f32_32x32x16_bf16 v[32:47], v[80:83], v[92:95], v[32:47]
	ds_read_b128 v[72:75], v127 offset:0
	v_mfma_f32_32x32x16_bf16 v[16:31], v[84:87], v[88:91], v[16:31]
	ds_read_b128 v[76:79], v127 offset:4096
	v_mfma_f32_32x32x16_bf16 v[0:15], v[84:87], v[92:95], v[0:15]
	ds_read_b128 v[68:71], v123 offset:4096
	s_waitcnt lgkmcnt(4)
	v_mfma_f32_32x32x16_bf16 v[48:63], v[96:99], v[104:107], v[48:63]
	v_mfma_f32_32x32x16_bf16 v[32:47], v[96:99], v[108:111], v[32:47]
	v_mfma_f32_32x32x16_bf16 v[16:31], v[100:103], v[104:107], v[16:31]
	v_mfma_f32_32x32x16_bf16 v[0:15], v[100:103], v[108:111], v[0:15]
	s_waitcnt lgkmcnt(0)
	v_mfma_f32_32x32x16_bf16 v[48:63], v[64:67], v[72:75], v[48:63]
	v_mfma_f32_32x32x16_bf16 v[32:47], v[64:67], v[76:79], v[32:47]
	v_mfma_f32_32x32x16_bf16 v[16:31], v[68:71], v[72:75], v[16:31]
	v_mfma_f32_32x32x16_bf16 v[0:15], v[68:71], v[76:79], v[0:15]
	s_barrier
	s_add_u32 m0, s98, 0x0
	s_nop 0
	global_load_lds_dwordx4 v112, s[4:5] offset:0
	global_load_lds_dwordx4 v113, s[4:5] offset:1024
	global_load_lds_dwordx4 v114, s[4:5] offset:2048
	global_load_lds_dwordx4 v115, s[4:5] offset:3072
	s_add_u32 m0, s98, 0x1000
	s_nop 0
	global_load_lds_dwordx4 v116, s[4:5] offset:0
	global_load_lds_dwordx4 v117, s[4:5] offset:1024
	global_load_lds_dwordx4 v118, s[4:5] offset:2048
	global_load_lds_dwordx4 v119, s[4:5] offset:3072
	s_add_u32 s4, s4, 0x80
	s_addc_u32 s5, s5, 0
	s_waitcnt vmcnt(8)
	s_barrier
	ds_read_b128 v[64:67], v120 offset:32768
	ds_read_b128 v[72:75], v124 offset:32768
	ds_read_b128 v[76:79], v124 offset:36864
	ds_read_b128 v[68:71], v120 offset:36864
	ds_read_b128 v[80:83], v121 offset:32768
	ds_read_b128 v[88:91], v125 offset:32768
	ds_read_b128 v[92:95], v125 offset:36864
	ds_read_b128 v[84:87], v121 offset:36864
	s_waitcnt lgkmcnt(4)
	v_mfma_f32_32x32x16_bf16 v[48:63], v[64:67], v[72:75], v[48:63]
	ds_read_b128 v[96:99], v122 offset:32768
	v_mfma_f32_32x32x16_bf16 v[32:47], v[64:67], v[76:79], v[32:47]
	ds_read_b128 v[104:107], v126 offset:32768
	v_mfma_f32_32x32x16_bf16 v[16:31], v[68:71], v[72:75], v[16:31]
	ds_read_b128 v[108:111], v126 offset:36864
	v_mfma_f32_32x32x16_bf16 v[0:15], v[68:71], v[76:79], v[0:15]
	ds_read_b128 v[100:103], v122 offset:36864
	s_waitcnt lgkmcnt(4)
	v_mfma_f32_32x32x16_bf16 v[48:63], v[80:83], v[88:91], v[48:63]
	ds_read_b128 v[64:67], v123 offset:32768
	v_mfma_f32_32x32x16_bf16 v[32:47], v[80:83], v[92:95], v[32:47]
	ds_read_b128 v[72:75], v127 offset:32768
	v_mfma_f32_32x32x16_bf16 v[16:31], v[84:87], v[88:91], v[16:31]
	ds_read_b128 v[76:79], v127 offset:36864
	v_mfma_f32_32x32x16_bf16 v[0:15], v[84:87], v[92:95], v[0:15]
	ds_read_b128 v[68:71], v123 offset:36864
	s_waitcnt lgkmcnt(4)
	v_mfma_f32_32x32x16_bf16 v[48:63], v[96:99], v[104:107], v[48:63]
	v_mfma_f32_32x32x16_bf16 v[32:47], v[96:99], v[108:111], v[32:47]
	v_mfma_f32_32x32x16_bf16 v[16:31], v[100:103], v[104:107], v[16:31]
	v_mfma_f32_32x32x16_bf16 v[0:15], v[100:103], v[108:111], v[0:15]
	s_waitcnt lgkmcnt(0)
	v_mfma_f32_32x32x16_bf16 v[48:63], v[64:67], v[72:75], v[48:63]
	v_mfma_f32_32x32x16_bf16 v[32:47], v[64:67], v[76:79], v[32:47]
	v_mfma_f32_32x32x16_bf16 v[16:31], v[68:71], v[72:75], v[16:31]
	v_mfma_f32_32x32x16_bf16 v[0:15], v[68:71], v[76:79], v[0:15]
	s_barrier
	s_add_u32 m0, s98, 0x8000
	s_nop 0
	global_load_lds_dwordx4 v112, s[4:5] offset:0
	global_load_lds_dwordx4 v113, s[4:5] offset:1024
	global_load_lds_dwordx4 v114, s[4:5] offset:2048
	global_load_lds_dwordx4 v115, s[4:5] offset:3072
	s_add_u32 m0, s98, 0x9000
	s_nop 0
	global_load_lds_dwordx4 v116, s[4:5] offset:0
	global_load_lds_dwordx4 v117, s[4:5] offset:1024
	global_load_lds_dwordx4 v118, s[4:5] offset:2048
	global_load_lds_dwordx4 v119, s[4:5] offset:3072
	s_add_u32 s4, s4, 0x80
	s_addc_u32 s5, s5, 0
	s_sub_u32 s6, s6, 1
	s_cmp_lg_u32 s6, 0
	s_cbranch_scc1 .Lg6_loop
	s_waitcnt vmcnt(8)
	s_barrier
	ds_read_b128 v[64:67], v120 offset:0
	ds_read_b128 v[72:75], v124 offset:0
	ds_read_b128 v[76:79], v124 offset:4096
	ds_read_b128 v[68:71], v120 offset:4096
	ds_read_b128 v[80:83], v121 offset:0
	ds_read_b128 v[88:91], v125 offset:0
	ds_read_b128 v[92:95], v125 offset:4096
	ds_read_b128 v[84:87], v121 offset:4096
	s_waitcnt lgkmcnt(4)
	v_mfma_f32_32x32x16_bf16 v[48:63], v[64:67], v[72:75], v[48:63]
	ds_read_b128 v[96:99], v122 offset:0
	v_mfma_f32_32x32x16_bf16 v[32:47], v[64:67], v[76:79], v[32:47]
	ds_read_b128 v[104:107], v126 offset:0
	v_mfma_f32_32x32x16_bf16 v[16:31], v[68:71], v[72:75], v[16:31]
	ds_read_b128 v[108:111], v126 offset:4096
	v_mfma_f32_32x32x16_bf16 v[0:15], v[68:71], v[76:79], v[0:15]
	ds_read_b128 v[100:103], v122 offset:4096
	s_waitcnt lgkmcnt(4)
	v_mfma_f32_32x32x16_bf16 v[48:63], v[80:83], v[88:91], v[48:63]
	ds_read_b128 v[64:67], v123 offset:0
	v_mfma_f32_32x32x16_bf16 v[32:47], v[80:83], v[92:95], v[32:47]
	ds_read_b128 v[72:75], v127 offset:0
	v_mfma_f32_32x32x16_bf16 v[16:31], v[84:87], v[88:91], v[16:31]
	ds_read_b128 v[76:79], v127 offset:4096
	v_mfma_f32_32x32x16_bf16 v[0:15], v[84:87], v[92:95], v[0:15]
	ds_read_b128 v[68:71], v123 offset:4096
	s_waitcnt lgkmcnt(4)
	v_mfma_f32_32x32x16_bf16 v[48:63], v[96:99], v[104:107], v[48:63]
	v_mfma_f32_32x32x16_bf16 v[32:47], v[96:99], v[108:111], v[32:47]
	v_mfma_f32_32x32x16_bf16 v[16:31], v[100:103], v[104:107], v[16:31]
	v_mfma_f32_32x32x16_bf16 v[0:15], v[100:103], v[108:111], v[0:15]
	s_waitcnt lgkmcnt(0)
	v_mfma_f32_32x32x16_bf16 v[48:63], v[64:67], v[72:75], v[48:63]
	v_mfma_f32_32x32x16_bf16 v[32:47], v[64:67], v[76:79], v[32:47]
	v_mfma_f32_32x32x16_bf16 v[16:31], v[68:71], v[72:75], v[16:31]
	v_mfma_f32_32x32x16_bf16 v[0:15], v[68:71], v[76:79], v[0:15]
	s_barrier
	s_waitcnt vmcnt(0)
	s_barrier
	ds_read_b128 v[64:67], v120 offset:32768
	ds_read_b128 v[72:75], v124 offset:32768
	ds_read_b128 v[76:79], v124 offset:36864
	ds_read_b128 v[68:71], v120 offset:36864
	ds_read_b128 v[80:83], v121 offset:32768
	ds_read_b128 v[88:91], v125 offset:32768
	ds_read_b128 v[92:95], v125 offset:36864
	ds_read_b128 v[84:87], v121 offset:36864
	s_waitcnt lgkmcnt(4)
	v_mfma_f32_32x32x16_bf16 v[48:63], v[64:67], v[72:75], v[48:63]
	ds_read_b128 v[96:99], v122 offset:32768
	v_mfma_f32_32x32x16_bf16 v[32:47], v[64:67], v[76:79], v[32:47]
	ds_read_b128 v[104:107], v126 offset:32768
	v_mfma_f32_32x32x16_bf16 v[16:31], v[68:71], v[72:75], v[16:31]
	ds_read_b128 v[108:111], v126 offset:36864
	v_mfma_f32_32x32x16_bf16 v[0:15], v[68:71], v[76:79], v[0:15]
	ds_read_b128 v[100:103], v122 offset:36864
	s_waitcnt lgkmcnt(4)
	v_mfma_f32_32x32x16_bf16 v[48:63], v[80:83], v[88:91], v[48:63]
	ds_read_b128 v[64:67], v123 offset:32768
	v_mfma_f32_32x32x16_bf16 v[32:47], v[80:83], v[92:95], v[32:47]
	ds_read_b128 v[72:75], v127 offset:32768
	v_mfma_f32_32x32x16_bf16 v[16:31], v[84:87], v[88:91], v[16:31]
	ds_read_b128 v[76:79], v127 offset:36864
	v_mfma_f32_32x32x16_bf16 v[0:15], v[84:87], v[92:95], v[0:15]
	ds_read_b128 v[68:71], v123 offset:36864
	s_waitcnt lgkmcnt(4)
	v_mfma_f32_32x32x16_bf16 v[48:63], v[96:99], v[104:107], v[48:63]
	v_mfma_f32_32x32x16_bf16 v[32:47], v[96:99], v[108:111], v[32:47]
	v_mfma_f32_32x32x16_bf16 v[16:31], v[100:103], v[104:107], v[16:31]
	v_mfma_f32_32x32x16_bf16 v[0:15], v[100:103], v[108:111], v[0:15]
	s_waitcnt lgkmcnt(0)
	v_mfma_f32_32x32x16_bf16 v[48:63], v[64:67], v[72:75], v[48:63]
	v_mfma_f32_32x32x16_bf16 v[32:47], v[64:67], v[76:79], v[32:47]
	v_mfma_f32_32x32x16_bf16 v[16:31], v[68:71], v[72:75], v[16:31]
	v_mfma_f32_32x32x16_bf16 v[0:15], v[68:71], v[76:79], v[0:15]
	s_nop 7
	s_nop 7
	s_branch .LBB0_2283

.LBB0_2352:
	ds_read_b128 v[144:147], v185
	ds_read_b128 v[156:159], v185 offset:4608
	ds_read_b128 v[152:155], v187 offset:36864
	ds_read_b128 v[160:163], v187 offset:41472
	s_add_i32 s10, s10, 3
	s_cmp_ge_u32 s10, s6
	s_waitcnt lgkmcnt(1)
	v_mfma_f32_32x32x16_bf16 v[48:63], v[144:147], v[152:155], v[48:63]
	ds_read_b128 v[164:167], v185 offset:32
	s_waitcnt lgkmcnt(1)
	v_mfma_f32_32x32x16_bf16 v[16:31], v[144:147], v[160:163], v[16:31]
	ds_read_b128 v[144:147], v187 offset:36896
	v_mfma_f32_32x32x16_bf16 v[32:47], v[156:159], v[152:155], v[32:47]
	ds_read_b128 v[152:155], v185 offset:4640
	v_mfma_f32_32x32x16_bf16 v[0:15], v[156:159], v[160:163], v[0:15]
	ds_read_b128 v[156:159], v187 offset:41504
	s_waitcnt lgkmcnt(2)
	v_mfma_f32_32x32x16_bf16 v[48:63], v[164:167], v[144:147], v[48:63]
	ds_read_b128 v[160:163], v185 offset:64
	s_waitcnt lgkmcnt(1)
	v_mfma_f32_32x32x16_bf16 v[16:31], v[164:167], v[156:159], v[16:31]
	ds_read_b128 v[164:167], v185 offset:4672
	v_mfma_f32_32x32x16_bf16 v[32:47], v[152:155], v[144:147], v[32:47]
	ds_read_b128 v[144:147], v187 offset:36928
	v_mfma_f32_32x32x16_bf16 v[0:15], v[152:155], v[156:159], v[0:15]
	ds_read_b128 v[152:155], v187 offset:41536
	s_waitcnt lgkmcnt(1)
	v_mfma_f32_32x32x16_bf16 v[48:63], v[160:163], v[144:147], v[48:63]
	ds_read_b128 v[156:159], v185 offset:96
	s_waitcnt lgkmcnt(1)
	v_mfma_f32_32x32x16_bf16 v[16:31], v[160:163], v[152:155], v[16:31]
	ds_read_b128 v[160:163], v185 offset:4704
	v_mfma_f32_32x32x16_bf16 v[32:47], v[164:167], v[144:147], v[32:47]
	ds_read_b128 v[144:147], v187 offset:36960
	v_mfma_f32_32x32x16_bf16 v[0:15], v[164:167], v[152:155], v[0:15]
	ds_read_b128 v[152:155], v187 offset:41568
	s_waitcnt lgkmcnt(1)
	v_mfma_f32_32x32x16_bf16 v[48:63], v[156:159], v[144:147], v[48:63]
	s_cbranch_scc1 .Lgw7_last
	s_waitcnt vmcnt(8)
	s_branch .Lgw7_go

.Lgw7_go:
	ds_write_b128 v188, v[88:91] offset:18432
	s_waitcnt lgkmcnt(1)
	v_mfma_f32_32x32x16_bf16 v[16:31], v[156:159], v[152:155], v[16:31]
	ds_write_b128 v188, v[92:95] offset:23040
	v_mfma_f32_32x32x16_bf16 v[32:47], v[160:163], v[144:147], v[32:47]
	ds_write_b128 v188, v[104:107] offset:27648
	v_mfma_f32_32x32x16_bf16 v[0:15], v[160:163], v[152:155], v[0:15]
	ds_write_b128 v188, v[112:115] offset:32256
	ds_write_b128 v188, v[108:111] offset:55296
	ds_write_b128 v188, v[116:119] offset:59904
	ds_write_b128 v188, v[120:123] offset:64512
	ds_write_b128 v189, v[124:127] offset:13824
	s_waitcnt lgkmcnt(0)
	s_barrier
	s_cbranch_scc1 .LBB0_2354
	v_add_co_u32_e32 v88, vcc, 0x3971000, v142
	s_nop 1
	v_addc_co_u32_e32 v89, vcc, 0, v143, vcc
	v_add_co_u32_e32 v92, vcc, 0x399d000, v142
	s_nop 1
	v_addc_co_u32_e32 v93, vcc, 0, v143, vcc
	v_add_co_u32_e32 v104, vcc, 0x39c9000, v142
	global_load_dwordx4 v[88:91], v[88:89], off offset:2688
	s_nop 0
	global_load_dwordx4 v[92:95], v[92:93], off offset:2688
	v_addc_co_u32_e32 v105, vcc, 0, v143, vcc
	v_add_co_u32_e32 v108, vcc, 0x39f5000, v142
	s_nop 1
	v_addc_co_u32_e32 v109, vcc, 0, v143, vcc
	global_load_dwordx4 v[104:107], v[104:105], off offset:2688
	s_nop 0
	global_load_dwordx4 v[112:115], v[108:109], off offset:2688
	v_add_co_u32_e32 v108, vcc, 0x26c0000, v140
	s_nop 1
	v_addc_co_u32_e32 v109, vcc, 0, v141, vcc
	v_add_co_u32_e32 v116, vcc, 0x26ec000, v140
	s_nop 1
	v_addc_co_u32_e32 v117, vcc, 0, v141, vcc
	v_add_co_u32_e32 v120, vcc, 0x2718000, v140
	global_load_dwordx4 v[108:111], v[108:109], off offset:384
	s_nop 0
	global_load_dwordx4 v[116:119], v[116:117], off offset:384
	v_addc_co_u32_e32 v121, vcc, 0, v141, vcc
	v_add_co_u32_e32 v124, vcc, 0x2744000, v140
	s_nop 1
	v_addc_co_u32_e32 v125, vcc, 0, v141, vcc
	global_load_dwordx4 v[120:123], v[120:121], off offset:384
	s_nop 0
	global_load_dwordx4 v[124:127], v[124:125], off offset:384
.LBB0_2354:
	ds_read_b128 v[140:143], v185 offset:18432
	ds_read_b128 v[152:155], v185 offset:23040
	ds_read_b128 v[144:147], v187 offset:55296
	ds_read_b128 v[156:159], v187 offset:59904
	s_andn2_b64 vcc, exec, s[4:5]
	s_waitcnt lgkmcnt(1)
	v_mfma_f32_32x32x16_bf16 v[48:63], v[140:143], v[144:147], v[48:63]
	ds_read_b128 v[160:163], v185 offset:18464
	s_waitcnt lgkmcnt(1)
	v_mfma_f32_32x32x16_bf16 v[16:31], v[140:143], v[156:159], v[16:31]
	ds_read_b128 v[140:143], v187 offset:55328
	v_mfma_f32_32x32x16_bf16 v[32:47], v[152:155], v[144:147], v[32:47]
	ds_read_b128 v[144:147], v185 offset:23072
	v_mfma_f32_32x32x16_bf16 v[0:15], v[152:155], v[156:159], v[0:15]
	ds_read_b128 v[152:155], v187 offset:59936
	s_waitcnt lgkmcnt(2)
	v_mfma_f32_32x32x16_bf16 v[48:63], v[160:163], v[140:143], v[48:63]
	ds_read_b128 v[156:159], v185 offset:18496
	s_waitcnt lgkmcnt(1)
	v_mfma_f32_32x32x16_bf16 v[16:31], v[160:163], v[152:155], v[16:31]
	ds_read_b128 v[160:163], v185 offset:23104
	v_mfma_f32_32x32x16_bf16 v[32:47], v[144:147], v[140:143], v[32:47]
	ds_read_b128 v[140:143], v187 offset:55360
	v_mfma_f32_32x32x16_bf16 v[0:15], v[144:147], v[152:155], v[0:15]
	ds_read_b128 v[144:147], v187 offset:59968
	s_waitcnt lgkmcnt(1)
	v_mfma_f32_32x32x16_bf16 v[48:63], v[156:159], v[140:143], v[48:63]
	ds_read_b128 v[152:155], v185 offset:18528
	s_waitcnt lgkmcnt(1)
	v_mfma_f32_32x32x16_bf16 v[16:31], v[156:159], v[144:147], v[16:31]
	ds_read_b128 v[156:159], v185 offset:23136
	v_mfma_f32_32x32x16_bf16 v[32:47], v[160:163], v[140:143], v[32:47]
	ds_read_b128 v[140:143], v187 offset:55392
	v_mfma_f32_32x32x16_bf16 v[0:15], v[160:163], v[144:147], v[0:15]
	ds_read_b128 v[144:147], v187 offset:60000
	s_waitcnt lgkmcnt(1)
	v_mfma_f32_32x32x16_bf16 v[48:63], v[152:155], v[140:143], v[48:63]
	s_waitcnt lgkmcnt(0)
	v_mfma_f32_32x32x16_bf16 v[16:31], v[152:155], v[144:147], v[16:31]
	v_mfma_f32_32x32x16_bf16 v[32:47], v[156:159], v[140:143], v[32:47]
	v_mfma_f32_32x32x16_bf16 v[0:15], v[156:159], v[144:147], v[0:15]
	s_cbranch_vccnz .LBB0_2349
	s_waitcnt vmcnt(8)
	ds_write_b128 v188, v[64:67]
	ds_write_b128 v188, v[68:71] offset:4608
	ds_write_b128 v188, v[72:75] offset:9216
	ds_write_b128 v188, v[80:83] offset:13824
	ds_write_b128 v188, v[76:79] offset:36864
	ds_write_b128 v188, v[84:87] offset:41472
	ds_write_b128 v188, v[96:99] offset:46080
	ds_write_b128 v188, v[100:103] offset:50688
	s_branch .LBB0_2349

	.amdhsa_kernel _Z4mega6Params
		.amdhsa_group_segment_fixed_size 77840
		.amdhsa_private_segment_fixed_size 0
		.amdhsa_kernarg_size 496
		.amdhsa_user_sgpr_count 2
		.amdhsa_user_sgpr_dispatch_ptr 0
		.amdhsa_user_sgpr_queue_ptr 0
		.amdhsa_user_sgpr_kernarg_segment_ptr 1
		.amdhsa_user_sgpr_dispatch_id 0
		.amdhsa_user_sgpr_kernarg_preload_length 0
		.amdhsa_user_sgpr_kernarg_preload_offset 0
		.amdhsa_user_sgpr_private_segment_size 0
		.amdhsa_uses_dynamic_stack 0
		.amdhsa_enable_private_segment 0
		.amdhsa_system_sgpr_workgroup_id_x 1
		.amdhsa_system_sgpr_workgroup_id_y 0
		.amdhsa_system_sgpr_workgroup_id_z 0
		.amdhsa_system_sgpr_workgroup_info 0
		.amdhsa_system_vgpr_workitem_id 2
		.amdhsa_next_free_vgpr 251
		.amdhsa_next_free_sgpr 102
		.amdhsa_accum_offset 252
		.amdhsa_reserve_vcc 1
		.amdhsa_float_round_mode_32 0
		.amdhsa_float_round_mode_16_64 0
		.amdhsa_float_denorm_mode_32 3
		.amdhsa_float_denorm_mode_16_64 3
		.amdhsa_dx10_clamp 1
		.amdhsa_ieee_mode 1
		.amdhsa_fp16_overflow 0
		.amdhsa_tg_split 0
		.amdhsa_exception_fp_ieee_invalid_op 0
		.amdhsa_exception_fp_denorm_src 0
		.amdhsa_exception_fp_ieee_div_zero 0
		.amdhsa_exception_fp_ieee_overflow 0
		.amdhsa_exception_fp_ieee_underflow 0
		.amdhsa_exception_fp_ieee_inexact 0
		.amdhsa_exception_int_div_zero 0
	.end_amdhsa_kernel

amdhsa.kernels:
  - .agpr_count:     0
    .args:
      - .offset:         0
        .size:           240
        .value_kind:     by_value
      - .offset:         240
        .size:           4
        .value_kind:     hidden_block_count_x
      - .offset:         244
        .size:           4
        .value_kind:     hidden_block_count_y
      - .offset:         248
        .size:           4
        .value_kind:     hidden_block_count_z
      - .offset:         252
        .size:           2
        .value_kind:     hidden_group_size_x
      - .offset:         254
        .size:           2
        .value_kind:     hidden_group_size_y
      - .offset:         256
        .size:           2
        .value_kind:     hidden_group_size_z
      - .offset:         258
        .size:           2
        .value_kind:     hidden_remainder_x
      - .offset:         260
        .size:           2
        .value_kind:     hidden_remainder_y
      - .offset:         262
        .size:           2
        .value_kind:     hidden_remainder_z
      - .offset:         280
        .size:           8
        .value_kind:     hidden_global_offset_x
      - .offset:         288
        .size:           8
        .value_kind:     hidden_global_offset_y
      - .offset:         296
        .size:           8
        .value_kind:     hidden_global_offset_z
      - .offset:         304
        .size:           2
        .value_kind:     hidden_grid_dims
      - .offset:         328
        .size:           8
        .value_kind:     hidden_multigrid_sync_arg
    .group_segment_fixed_size: 77840
    .kernarg_segment_align: 8
    .kernarg_segment_size: 496
    .language:       OpenCL C
    .language_version:
      - 2
      - 0
    .max_flat_workgroup_size: 256
    .name:           _Z4mega6Params
    .private_segment_fixed_size: 0
    .sgpr_count:     108
    .sgpr_spill_count: 192
    .symbol:         _Z4mega6Params.kd
    .uniform_work_group_size: 1
    .uses_dynamic_stack: false
    .vgpr_count:     251
    .vgpr_spill_count: 0
    .wavefront_size: 64
